# grid barrier: XCD leader bumps the per-XCD generation before its own cache invalidate; sq-relu epilogue drops self-canonicalising v_max
# speedup vs baseline: 1.0074x; 1.0049x over previous
; __device__ __forceinline__ unsigned xb_ld(unsigned* p)              { return __hip_atomic_load(p, __ATOMIC_RELAXED, __HIP_MEMORY_SCOPE_AGENT); }
; __device__ __forceinline__ unsigned xb_add(unsigned* p, unsigned v) { return __hip_atomic_fetch_add(p, v, __ATOMIC_RELAXED, __HIP_MEMORY_SCOPE_AGENT); }
; #define XB_SPIN(cond, bar) do { unsigned _sp = 0; while (cond) { __builtin_amdgcn_s_sleep(1); \
;     if ((++_sp & 255u) == 0u) { if (xb_ld(&(bar)[XB_TMO])) break; if (_sp > XB_SPIN_CAP) { atomicAdd(&(bar)[XB_TMO], 1u); break; } } } } while (0)
; __device__ __forceinline__ void xcd_barrier(const XcdBarrier& b) {
;     ...
;         if (old + 1u == (gen + 1u) * nloc) {
;             __builtin_amdgcn_fence(__ATOMIC_RELEASE, "agent");
;             asm volatile("s_waitcnt vmcnt(0)" ::: "memory");
;             const unsigned og = xb_add(&bar[XB_TOP], 1u);
;             const unsigned tg = og / nx;
;             if (og + 1u == (tg + 1u) * nx) xb_add(&bar[XB_TOPGEN], 1u);
;             else XB_SPIN(xb_ld(&bar[XB_TOPGEN]) == tg, bar);
;             __builtin_amdgcn_fence(__ATOMIC_ACQUIRE, "agent");
;             xb_add(&bar[XB_XGEN(b.x)], 1u);
;             asm volatile("s_waitcnt vmcnt(0)" ::: "memory");
.LBB0_113:
	s_or_b64 exec, exec, s[8:9]
	s_mov_b64 s[8:9], exec
	v_mbcnt_lo_u32_b32 v0, s8, 0
	v_mbcnt_hi_u32_b32 v0, s9, v0
	v_cmp_eq_u32_e32 vcc, 0, v0
	s_waitcnt vmcnt(0)
	s_and_saveexec_b64 s[10:11], vcc
	s_cbranch_execz .LBB0_115
	s_bcnt1_i32_b64 s8, s[8:9]
	v_mov_b32_e32 v0, 0x2000
	v_mov_b32_e32 v1, s8
	global_atomic_add v0, v1, s[2:3] offset:1024
.LBB0_115:
	s_or_b64 exec, exec, s[10:11]
	buffer_inv sc1
	s_waitcnt vmcnt(0)

; __device__ __forceinline__ unsigned xb_ld(unsigned* p)              { return __hip_atomic_load(p, __ATOMIC_RELAXED, __HIP_MEMORY_SCOPE_AGENT); }
; __device__ __forceinline__ unsigned xb_add(unsigned* p, unsigned v) { return __hip_atomic_fetch_add(p, v, __ATOMIC_RELAXED, __HIP_MEMORY_SCOPE_AGENT); }
; #define XB_SPIN(cond, bar) do { unsigned _sp = 0; while (cond) { __builtin_amdgcn_s_sleep(1); \
;     if ((++_sp & 255u) == 0u) { if (xb_ld(&(bar)[XB_TMO])) break; if (_sp > XB_SPIN_CAP) { atomicAdd(&(bar)[XB_TMO], 1u); break; } } } } while (0)
; __device__ __forceinline__ void xcd_barrier(const XcdBarrier& b) {
;     ...
;         if (old + 1u == (gen + 1u) * nloc) {
;             __builtin_amdgcn_fence(__ATOMIC_RELEASE, "agent");
;             asm volatile("s_waitcnt vmcnt(0)" ::: "memory");
;             const unsigned og = xb_add(&bar[XB_TOP], 1u);
;             const unsigned tg = og / nx;
;             if (og + 1u == (tg + 1u) * nx) xb_add(&bar[XB_TOPGEN], 1u);
;             else XB_SPIN(xb_ld(&bar[XB_TOPGEN]) == tg, bar);
;             __builtin_amdgcn_fence(__ATOMIC_ACQUIRE, "agent");
;             xb_add(&bar[XB_XGEN(b.x)], 1u);
;             asm volatile("s_waitcnt vmcnt(0)" ::: "memory");
.LBB0_171:
	s_or_b64 exec, exec, s[6:7]
	s_mov_b64 s[6:7], exec
	v_mbcnt_lo_u32_b32 v0, s6, 0
	v_mbcnt_hi_u32_b32 v0, s7, v0
	v_cmp_eq_u32_e32 vcc, 0, v0
	s_waitcnt vmcnt(0)
	s_and_saveexec_b64 s[8:9], vcc
	s_cbranch_execz .LBB0_173
	s_bcnt1_i32_b64 s5, s[6:7]
	v_mov_b32_e32 v0, 0x2000
	v_mov_b32_e32 v1, s5
	global_atomic_add v0, v1, s[2:3] offset:1024
.LBB0_173:
	s_or_b64 exec, exec, s[8:9]
	buffer_inv sc1
	s_waitcnt vmcnt(0)

; __device__ __forceinline__ unsigned xb_ld(unsigned* p)              { return __hip_atomic_load(p, __ATOMIC_RELAXED, __HIP_MEMORY_SCOPE_AGENT); }
; __device__ __forceinline__ unsigned xb_add(unsigned* p, unsigned v) { return __hip_atomic_fetch_add(p, v, __ATOMIC_RELAXED, __HIP_MEMORY_SCOPE_AGENT); }
; #define XB_SPIN(cond, bar) do { unsigned _sp = 0; while (cond) { __builtin_amdgcn_s_sleep(1); \
;     if ((++_sp & 255u) == 0u) { if (xb_ld(&(bar)[XB_TMO])) break; if (_sp > XB_SPIN_CAP) { atomicAdd(&(bar)[XB_TMO], 1u); break; } } } } while (0)
; __device__ __forceinline__ void xcd_barrier(const XcdBarrier& b) {
;     ...
;         if (old + 1u == (gen + 1u) * nloc) {
;             __builtin_amdgcn_fence(__ATOMIC_RELEASE, "agent");
;             asm volatile("s_waitcnt vmcnt(0)" ::: "memory");
;             const unsigned og = xb_add(&bar[XB_TOP], 1u);
;             const unsigned tg = og / nx;
;             if (og + 1u == (tg + 1u) * nx) xb_add(&bar[XB_TOPGEN], 1u);
;             else XB_SPIN(xb_ld(&bar[XB_TOPGEN]) == tg, bar);
;             __builtin_amdgcn_fence(__ATOMIC_ACQUIRE, "agent");
;             xb_add(&bar[XB_XGEN(b.x)], 1u);
;             asm volatile("s_waitcnt vmcnt(0)" ::: "memory");
.LBB0_304:
	s_or_b64 exec, exec, s[4:5]
	s_mov_b64 s[4:5], exec
	v_mbcnt_lo_u32_b32 v0, s4, 0
	v_mbcnt_hi_u32_b32 v0, s5, v0
	v_cmp_eq_u32_e32 vcc, 0, v0
	s_waitcnt vmcnt(0)
	s_and_saveexec_b64 s[6:7], vcc
	s_cbranch_execz .LBB0_306
	s_bcnt1_i32_b64 s4, s[4:5]
	v_mov_b32_e32 v0, 0x2000
	v_mov_b32_e32 v1, s4
	global_atomic_add v0, v1, s[2:3] offset:1024
.LBB0_306:
	s_or_b64 exec, exec, s[6:7]
	buffer_inv sc1
	s_waitcnt vmcnt(0)

; #define PG8_STAGE(bufoff, gbase, voff) do { _Pragma("unroll") for (int _i = 0; _i < 2; ++_i) \
;         __builtin_amdgcn_global_load_lds((const unsigned*)((const char*)(gbase) + (voff)[_i]), (LAS unsigned*)(lds + (bufoff) + ldsw + _i * 8192), 16, 0, 0); } while (0)
; #define PG8_LDA(dst, b, h) do { _Pragma("unroll") for (int m = 0; m < 4; ++m) _Pragma("unroll") for (int k = 0; k < 2; ++k) dst[m][k] = *(const LAS bf16x8*)(lds + PG8_SA(b, h) + aoff + m * 2048 + k * 1024); } while (0)
; #define PG8_LDB(dst, b, h) do { _Pragma("unroll") for (int n = 0; n < 2; ++n) _Pragma("unroll") for (int k = 0; k < 2; ++k) dst[n][k] = *(const LAS bf16x8*)(lds + PG8_SB(b, h) + boff + n * 2048 + k * 1024); } while (0)
; #define PG8_WAIT_V(n) asm volatile("s_waitcnt vmcnt(" #n ")" ::: "memory")
; #define PG8_WAIT_L(n) asm volatile("s_waitcnt lgkmcnt(" #n ")" ::: "memory")
; #define PG8_BAR __builtin_amdgcn_s_barrier()
; #define PG8_SCHED __builtin_amdgcn_sched_barrier(0)
; template <class Epi>
; __device__ __forceinline__ void gemm_phase(LAS unsigned char* lds, const bf16_t* A, int lda, const bf16_t* Bt, int ldb, int M, int N, int K, int asel, const Epi& E, const int fixed_round = -1) {
;     ...
;         for (int t = 0; t < nt; t += 2) {
;             const bool last = (t == nt - 2);
;             const char* a1 = cA + (size_t)(t + 1) * kstep;
;             const char* a2 = last ? nA : cA + (size_t)(t + 2) * kstep; const char* b2 = last ? nB : cB + (size_t)(t + 2) * kstep;
;             const char* a3 = a2 + kstep; const char* b3 = b2 + kstep;
;             PG8_LDB(B0, 0, 0); PG8_SCHED; PG8_LDA(At, 0, 0); PG8_STAGE(PG8_SA(1, 1), a1 + hstepA, voffA);
;             PG8_WAIT_L(8); PG8_BAR; PG8_WAIT_L(0); PG8_MMA(0, 0, At, B0); PG8_BAR; PG8_SCHED;
;             PG8_LDB(B1, 0, 1); PG8_STAGE(PG8_SB(0, 0), b2, voffB);
;             PG8_BAR; PG8_WAIT_L(0); PG8_MMA(0, 1, At, B1); PG8_BAR;
;             PG8_LDA(At, 0, 1); PG8_STAGE(PG8_SA(0, 0), a2, voffA);
;             PG8_BAR; PG8_WAIT_L(0); PG8_MMA(1, 0, At, B0); PG8_BAR; PG8_SCHED;
;             PG8_STAGE(PG8_SB(0, 1), b2 + hstepB, voffB);
;             PG8_WAIT_V(6); PG8_BAR; PG8_MMA(1, 1, At, B1); PG8_BAR;
.LBB0_591:
	ds_read_b128 v[152:155], v149
	ds_read_b128 v[156:159], v149 offset:1024
	ds_read_b128 v[160:163], v149 offset:2048
	ds_read_b128 v[164:167], v149 offset:3072
	s_add_u32 s28, s30, 0xfff80080
	s_addc_u32 s29, s31, -1
	s_cmp_eq_u32 s56, 28
	s_cselect_b32 s37, s7, s29
	s_cselect_b32 s36, s52, s28
	s_cselect_b32 s35, s5, s55
	s_cselect_b32 s34, s53, s54
	s_add_i32 m0, s27, 0xc000
	ds_read_b128 v[168:171], v150
	ds_read_b128 v[172:175], v150 offset:1024
	ds_read_b128 v[176:179], v150 offset:2048
	ds_read_b128 v[180:183], v150 offset:3072
	ds_read_b128 v[184:187], v150 offset:4096
	ds_read_b128 v[188:191], v150 offset:5120
	ds_read_b128 v[192:195], v150 offset:6144
	ds_read_b128 v[196:199], v150 offset:7168
	global_load_lds_dwordx4 v136, s[30:31]
	s_add_i32 m0, s27, 0xe000
	s_nop 0
	global_load_lds_dwordx4 v138, s[30:31]
	s_waitcnt lgkmcnt(8)
	s_barrier
	s_waitcnt lgkmcnt(0)
	s_setprio 1
	s_waitcnt lgkmcnt(0)
	v_mfma_f32_16x16x32_bf16 v[124:127], v[152:155], v[168:171], v[124:127]
	v_mfma_f32_16x16x32_bf16 v[120:123], v[160:163], v[168:171], v[120:123]
	v_mfma_f32_16x16x32_bf16 v[108:111], v[152:155], v[176:179], v[108:111]
	v_mfma_f32_16x16x32_bf16 v[104:107], v[160:163], v[176:179], v[104:107]
	v_mfma_f32_16x16x32_bf16 v[92:95], v[152:155], v[184:187], v[92:95]
	v_mfma_f32_16x16x32_bf16 v[88:91], v[160:163], v[184:187], v[88:91]
	v_mfma_f32_16x16x32_bf16 v[76:79], v[152:155], v[192:195], v[76:79]
	v_mfma_f32_16x16x32_bf16 v[72:75], v[160:163], v[192:195], v[72:75]
	v_mfma_f32_16x16x32_bf16 v[124:127], v[156:159], v[172:175], v[124:127]
	v_mfma_f32_16x16x32_bf16 v[120:123], v[164:167], v[172:175], v[120:123]
	v_mfma_f32_16x16x32_bf16 v[108:111], v[156:159], v[180:183], v[108:111]
	v_mfma_f32_16x16x32_bf16 v[104:107], v[164:167], v[180:183], v[104:107]
	v_mfma_f32_16x16x32_bf16 v[92:95], v[156:159], v[188:191], v[92:95]
	v_mfma_f32_16x16x32_bf16 v[88:91], v[164:167], v[188:191], v[88:91]
	v_mfma_f32_16x16x32_bf16 v[76:79], v[156:159], v[196:199], v[76:79]
	v_mfma_f32_16x16x32_bf16 v[72:75], v[164:167], v[196:199], v[72:75]
	s_setprio 0
	s_barrier
	s_add_i32 s28, s81, s42
	s_add_u32 s98, s34, s2
	s_addc_u32 s99, s35, s3
	s_mov_b32 m0, s28
	ds_read_b128 v[202:205], v151
	ds_read_b128 v[206:209], v151 offset:1024
	ds_read_b128 v[210:213], v151 offset:2048
	ds_read_b128 v[214:217], v151 offset:3072
	global_load_lds_dwordx4 v130, s[34:35]
	s_add_i32 m0, s28, 0x2000
	s_nop 0
	global_load_lds_dwordx4 v134, s[34:35]
	s_barrier
	s_waitcnt lgkmcnt(0)
	s_setprio 1
	s_waitcnt lgkmcnt(0)
	v_mfma_f32_16x16x32_bf16 v[116:119], v[202:205], v[168:171], v[116:119]
	v_mfma_f32_16x16x32_bf16 v[112:115], v[210:213], v[168:171], v[112:115]
	v_mfma_f32_16x16x32_bf16 v[100:103], v[202:205], v[176:179], v[100:103]
	v_mfma_f32_16x16x32_bf16 v[96:99], v[210:213], v[176:179], v[96:99]
	v_mfma_f32_16x16x32_bf16 v[84:87], v[202:205], v[184:187], v[84:87]
	v_mfma_f32_16x16x32_bf16 v[80:83], v[210:213], v[184:187], v[80:83]
	v_mfma_f32_16x16x32_bf16 v[68:71], v[202:205], v[192:195], v[68:71]
	v_mfma_f32_16x16x32_bf16 v[64:67], v[210:213], v[192:195], v[64:67]
	v_mfma_f32_16x16x32_bf16 v[116:119], v[206:209], v[172:175], v[116:119]
	v_mfma_f32_16x16x32_bf16 v[112:115], v[214:217], v[172:175], v[112:115]
	v_mfma_f32_16x16x32_bf16 v[100:103], v[206:209], v[180:183], v[100:103]
	v_mfma_f32_16x16x32_bf16 v[96:99], v[214:217], v[180:183], v[96:99]
	v_mfma_f32_16x16x32_bf16 v[84:87], v[206:209], v[188:191], v[84:87]
	v_mfma_f32_16x16x32_bf16 v[80:83], v[214:217], v[188:191], v[80:83]
	v_mfma_f32_16x16x32_bf16 v[68:71], v[206:209], v[196:199], v[68:71]
	v_mfma_f32_16x16x32_bf16 v[64:67], v[214:217], v[196:199], v[64:67]
	s_setprio 0
	s_mov_b32 m0, s27
	s_add_u32 s100, s36, s2
	s_addc_u32 s101, s37, s3
	s_barrier
	ds_read_b128 v[168:171], v150 offset:16384
	ds_read_b128 v[172:175], v150 offset:17408
	ds_read_b128 v[176:179], v150 offset:18432
	ds_read_b128 v[180:183], v150 offset:19456
	ds_read_b128 v[184:187], v150 offset:20480
	ds_read_b128 v[188:191], v150 offset:21504
	ds_read_b128 v[192:195], v150 offset:22528
	ds_read_b128 v[196:199], v150 offset:23552
	global_load_lds_dwordx4 v128, s[36:37]
	s_mov_b32 m0, s43
	s_nop 0
	global_load_lds_dwordx4 v132, s[36:37]
	s_barrier
	s_waitcnt lgkmcnt(0)
	s_setprio 1
	s_waitcnt lgkmcnt(0)
	v_mfma_f32_16x16x32_bf16 v[60:63], v[152:155], v[168:171], v[60:63]
	v_mfma_f32_16x16x32_bf16 v[56:59], v[160:163], v[168:171], v[56:59]
	v_mfma_f32_16x16x32_bf16 v[44:47], v[152:155], v[176:179], v[44:47]
	v_mfma_f32_16x16x32_bf16 v[40:43], v[160:163], v[176:179], v[40:43]
	v_mfma_f32_16x16x32_bf16 v[28:31], v[152:155], v[184:187], v[28:31]
	v_mfma_f32_16x16x32_bf16 v[24:27], v[160:163], v[184:187], v[24:27]
	v_mfma_f32_16x16x32_bf16 v[12:15], v[152:155], v[192:195], v[12:15]
	v_mfma_f32_16x16x32_bf16 v[8:11], v[160:163], v[192:195], v[8:11]
	v_mfma_f32_16x16x32_bf16 v[60:63], v[156:159], v[172:175], v[60:63]
	v_mfma_f32_16x16x32_bf16 v[56:59], v[164:167], v[172:175], v[56:59]
	v_mfma_f32_16x16x32_bf16 v[44:47], v[156:159], v[180:183], v[44:47]
	v_mfma_f32_16x16x32_bf16 v[40:43], v[164:167], v[180:183], v[40:43]
	v_mfma_f32_16x16x32_bf16 v[28:31], v[156:159], v[188:191], v[28:31]
	v_mfma_f32_16x16x32_bf16 v[24:27], v[164:167], v[188:191], v[24:27]
	v_mfma_f32_16x16x32_bf16 v[12:15], v[156:159], v[196:199], v[12:15]
	v_mfma_f32_16x16x32_bf16 v[8:11], v[164:167], v[196:199], v[8:11]
	s_setprio 0
	s_barrier
	s_add_u32 s28, s34, 0x80000
	s_addc_u32 s29, s35, 0
	s_add_i32 s57, s82, s42
	s_mov_b32 m0, s57
	s_nop 0
	global_load_lds_dwordx4 v130, s[28:29]
	s_add_i32 m0, s57, 0x2000
	s_nop 0
	global_load_lds_dwordx4 v134, s[28:29]
	s_waitcnt vmcnt(6)
	s_barrier
; #define PG8_STAGE(bufoff, gbase, voff) do { _Pragma("unroll") for (int _i = 0; _i < 2; ++_i) \
;         __builtin_amdgcn_global_load_lds((const unsigned*)((const char*)(gbase) + (voff)[_i]), (LAS unsigned*)(lds + (bufoff) + ldsw + _i * 8192), 16, 0, 0); } while (0)
; #define PG8_LDA(dst, b, h) do { _Pragma("unroll") for (int m = 0; m < 4; ++m) _Pragma("unroll") for (int k = 0; k < 2; ++k) dst[m][k] = *(const LAS bf16x8*)(lds + PG8_SA(b, h) + aoff + m * 2048 + k * 1024); } while (0)
; #define PG8_LDB(dst, b, h) do { _Pragma("unroll") for (int n = 0; n < 2; ++n) _Pragma("unroll") for (int k = 0; k < 2; ++k) dst[n][k] = *(const LAS bf16x8*)(lds + PG8_SB(b, h) + boff + n * 2048 + k * 1024); } while (0)
; #define PG8_WAIT_V(n) asm volatile("s_waitcnt vmcnt(" #n ")" ::: "memory")
; #define PG8_WAIT_L(n) asm volatile("s_waitcnt lgkmcnt(" #n ")" ::: "memory")
; #define PG8_BAR __builtin_amdgcn_s_barrier()
; #define PG8_SCHED __builtin_amdgcn_sched_barrier(0)
; template <class Epi>
; __device__ __forceinline__ void gemm_phase(LAS unsigned char* lds, const bf16_t* A, int lda, const bf16_t* Bt, int ldb, int M, int N, int K, int asel, const Epi& E, const int fixed_round = -1) {
;     ...
;             PG8_STAGE(PG8_SB(0, 1), b2 + hstepB, voffB);
;             PG8_WAIT_V(6); PG8_BAR; PG8_MMA(1, 1, At, B1); PG8_BAR;
;             PG8_LDB(B0, 1, 0); PG8_SCHED; PG8_LDA(At, 1, 0); PG8_STAGE(PG8_SA(0, 1), a2 + hstepA, voffA);
;             PG8_WAIT_L(8); PG8_BAR; PG8_WAIT_L(0); PG8_MMA(0, 0, At, B0); PG8_BAR; PG8_SCHED;
;             PG8_LDB(B1, 1, 1); PG8_STAGE(PG8_SB(1, 0), b3, voffB);
;             PG8_BAR; PG8_WAIT_L(0); PG8_MMA(0, 1, At, B1); PG8_BAR;
;             PG8_LDA(At, 1, 1); PG8_STAGE(PG8_SA(1, 0), a3, voffA);
;             PG8_BAR; PG8_WAIT_L(0); PG8_MMA(1, 0, At, B0); PG8_BAR; PG8_SCHED;
	s_setprio 1
	v_mfma_f32_16x16x32_bf16 v[52:55], v[202:205], v[168:171], v[52:55]
	v_mfma_f32_16x16x32_bf16 v[48:51], v[210:213], v[168:171], v[48:51]
	v_mfma_f32_16x16x32_bf16 v[36:39], v[202:205], v[176:179], v[36:39]
	v_mfma_f32_16x16x32_bf16 v[32:35], v[210:213], v[176:179], v[32:35]
	v_mfma_f32_16x16x32_bf16 v[20:23], v[202:205], v[184:187], v[20:23]
	v_mfma_f32_16x16x32_bf16 v[16:19], v[210:213], v[184:187], v[16:19]
	v_mfma_f32_16x16x32_bf16 v[4:7], v[202:205], v[192:195], v[4:7]
	v_mfma_f32_16x16x32_bf16 v[0:3], v[210:213], v[192:195], v[0:3]
	v_mfma_f32_16x16x32_bf16 v[52:55], v[206:209], v[172:175], v[52:55]
	v_mfma_f32_16x16x32_bf16 v[48:51], v[214:217], v[172:175], v[48:51]
	v_mfma_f32_16x16x32_bf16 v[36:39], v[206:209], v[180:183], v[36:39]
	v_mfma_f32_16x16x32_bf16 v[32:35], v[214:217], v[180:183], v[32:35]
	v_mfma_f32_16x16x32_bf16 v[20:23], v[206:209], v[188:191], v[20:23]
	v_mfma_f32_16x16x32_bf16 v[16:19], v[214:217], v[188:191], v[16:19]
	v_mfma_f32_16x16x32_bf16 v[4:7], v[206:209], v[196:199], v[4:7]
	v_mfma_f32_16x16x32_bf16 v[0:3], v[214:217], v[196:199], v[0:3]
	s_setprio 0
	v_add_u32_e32 v164, s83, v147
	s_barrier
	ds_read_b128 v[152:155], v164
	ds_read_b128 v[156:159], v164 offset:1024
	ds_read_b128 v[160:163], v164 offset:2048
	ds_read_b128 v[164:167], v164 offset:3072
	s_add_u32 s28, s36, 0x80000
	s_addc_u32 s29, s37, 0
	s_mov_b32 m0, s44
	ds_read_b128 v[168:171], v150 offset:32768
	ds_read_b128 v[172:175], v150 offset:33792
	ds_read_b128 v[176:179], v150 offset:34816
	ds_read_b128 v[180:183], v150 offset:35840
	ds_read_b128 v[184:187], v150 offset:36864
	ds_read_b128 v[188:191], v150 offset:37888
	ds_read_b128 v[192:195], v150 offset:38912
	ds_read_b128 v[196:199], v150 offset:39936
	global_load_lds_dwordx4 v128, s[28:29]
	s_mov_b32 m0, s45
	s_nop 0
	global_load_lds_dwordx4 v132, s[28:29]
	s_waitcnt lgkmcnt(8)
	s_barrier
	s_waitcnt lgkmcnt(0)
	s_setprio 1
	s_waitcnt lgkmcnt(0)
	v_mfma_f32_16x16x32_bf16 v[124:127], v[152:155], v[168:171], v[124:127]
	v_mfma_f32_16x16x32_bf16 v[120:123], v[160:163], v[168:171], v[120:123]
	v_mfma_f32_16x16x32_bf16 v[108:111], v[152:155], v[176:179], v[108:111]
	v_mfma_f32_16x16x32_bf16 v[104:107], v[160:163], v[176:179], v[104:107]
	v_mfma_f32_16x16x32_bf16 v[92:95], v[152:155], v[184:187], v[92:95]
	v_mfma_f32_16x16x32_bf16 v[88:91], v[160:163], v[184:187], v[88:91]
	v_mfma_f32_16x16x32_bf16 v[76:79], v[152:155], v[192:195], v[76:79]
	v_mfma_f32_16x16x32_bf16 v[72:75], v[160:163], v[192:195], v[72:75]
	v_mfma_f32_16x16x32_bf16 v[124:127], v[156:159], v[172:175], v[124:127]
	v_mfma_f32_16x16x32_bf16 v[120:123], v[164:167], v[172:175], v[120:123]
	v_mfma_f32_16x16x32_bf16 v[108:111], v[156:159], v[180:183], v[108:111]
	v_mfma_f32_16x16x32_bf16 v[104:107], v[164:167], v[180:183], v[104:107]
	v_mfma_f32_16x16x32_bf16 v[92:95], v[156:159], v[188:191], v[92:95]
	v_mfma_f32_16x16x32_bf16 v[88:91], v[164:167], v[188:191], v[88:91]
	v_mfma_f32_16x16x32_bf16 v[76:79], v[156:159], v[196:199], v[76:79]
	v_mfma_f32_16x16x32_bf16 v[72:75], v[164:167], v[196:199], v[72:75]
	s_setprio 0
	s_barrier
	s_add_i32 s28, s83, s42
	v_add_u32_e32 v214, s84, v147
	s_mov_b32 m0, s28
	ds_read_b128 v[202:205], v214
	ds_read_b128 v[206:209], v214 offset:1024
	ds_read_b128 v[210:213], v214 offset:2048
	ds_read_b128 v[214:217], v214 offset:3072
	global_load_lds_dwordx4 v130, s[98:99]
	s_add_i32 m0, s28, 0x2000
	s_nop 0
	global_load_lds_dwordx4 v134, s[98:99]
	s_barrier
	s_waitcnt lgkmcnt(0)
	s_setprio 1
	s_waitcnt lgkmcnt(0)
	v_mfma_f32_16x16x32_bf16 v[116:119], v[202:205], v[168:171], v[116:119]
	v_mfma_f32_16x16x32_bf16 v[112:115], v[210:213], v[168:171], v[112:115]
	v_mfma_f32_16x16x32_bf16 v[100:103], v[202:205], v[176:179], v[100:103]
	v_mfma_f32_16x16x32_bf16 v[96:99], v[210:213], v[176:179], v[96:99]
	v_mfma_f32_16x16x32_bf16 v[84:87], v[202:205], v[184:187], v[84:87]
	v_mfma_f32_16x16x32_bf16 v[80:83], v[210:213], v[184:187], v[80:83]
	v_mfma_f32_16x16x32_bf16 v[68:71], v[202:205], v[192:195], v[68:71]
	v_mfma_f32_16x16x32_bf16 v[64:67], v[210:213], v[192:195], v[64:67]
	v_mfma_f32_16x16x32_bf16 v[116:119], v[206:209], v[172:175], v[116:119]
	v_mfma_f32_16x16x32_bf16 v[112:115], v[214:217], v[172:175], v[112:115]
	v_mfma_f32_16x16x32_bf16 v[100:103], v[206:209], v[180:183], v[100:103]
	v_mfma_f32_16x16x32_bf16 v[96:99], v[214:217], v[180:183], v[96:99]
	v_mfma_f32_16x16x32_bf16 v[84:87], v[206:209], v[188:191], v[84:87]
	v_mfma_f32_16x16x32_bf16 v[80:83], v[214:217], v[188:191], v[80:83]
	v_mfma_f32_16x16x32_bf16 v[68:71], v[206:209], v[196:199], v[68:71]
	v_mfma_f32_16x16x32_bf16 v[64:67], v[214:217], v[196:199], v[64:67]
	s_setprio 0
	s_mov_b32 m0, s47
	s_barrier
	ds_read_b128 v[168:171], v150 offset:49152
	ds_read_b128 v[172:175], v150 offset:50176
	ds_read_b128 v[176:179], v150 offset:51200
	ds_read_b128 v[180:183], v150 offset:52224
	ds_read_b128 v[184:187], v150 offset:53248
	ds_read_b128 v[188:191], v150 offset:54272
	ds_read_b128 v[192:195], v150 offset:55296
	ds_read_b128 v[196:199], v150 offset:56320
	global_load_lds_dwordx4 v128, s[100:101]
	s_mov_b32 m0, s48
	s_nop 0
	global_load_lds_dwordx4 v132, s[100:101]
	s_barrier
; __device__ __forceinline__ unsigned cvt_pk_bf16(float lo, float hi) { const bf16x2_t r = __builtin_convertvector((f32x2){lo, hi}, bf16x2_t); return __builtin_bit_cast(unsigned, r); }
; #define PG8_STAGE(bufoff, gbase, voff) do { _Pragma("unroll") for (int _i = 0; _i < 2; ++_i) \
;         __builtin_amdgcn_global_load_lds((const unsigned*)((const char*)(gbase) + (voff)[_i]), (LAS unsigned*)(lds + (bufoff) + ldsw + _i * 8192), 16, 0, 0); } while (0)
; #define PG8_WAIT_V(n) asm volatile("s_waitcnt vmcnt(" #n ")" ::: "memory")
; #define PG8_WAIT_L(n) asm volatile("s_waitcnt lgkmcnt(" #n ")" ::: "memory")
; #define PG8_BAR __builtin_amdgcn_s_barrier()
; #define PG8_SCHED __builtin_amdgcn_sched_barrier(0)
; template <class Epi>
; __device__ __forceinline__ void gemm_phase(LAS unsigned char* lds, const bf16_t* A, int lda, const bf16_t* Bt, int ldb, int M, int N, int K, int asel, const Epi& E, const int fixed_round = -1) {
;     ...
;             PG8_BAR; PG8_WAIT_L(0); PG8_MMA(1, 0, At, B0); PG8_BAR; PG8_SCHED;
;             PG8_STAGE(PG8_SB(1, 1), b3 + hstepB, voffB);
;             PG8_WAIT_V(6); PG8_BAR; PG8_MMA(1, 1, At, B1); PG8_BAR;
;     __device__ __forceinline__ void operator()(const AccT& acc, const Unit& u, int wr, int wc, int fr, int fq) const {
;         const int row0 = u.pm * BM + wr * 64 + fr, col0 = u.pn * BM + wc * 32 + 8 * fq;
; #pragma unroll
;         for (int ai = 0; ai < 2; ++ai)
; #pragma unroll
;             for (int m = 0; m < 4; ++m) { bf16_t* rowp = O + (size_t)(row0 + ai * HALF + m * 16) * DFF + col0;
; #pragma unroll
;                 for (int bj = 0; bj < 2; ++bj) { f32x4 v0 = acc[ai][bj][m][0], v1 = acc[ai][bj][m][1];
; #pragma unroll
;                     for (int j = 0; j < 4; ++j) { float a = fmaxf(v0[j], 0.f), b = fmaxf(v1[j], 0.f); v0[j] = a * a; v1[j] = b * b; }
;                     u32x4 w; w.x = cvt_pk_bf16(v0[0], v0[1]); w.y = cvt_pk_bf16(v0[2], v0[3]); w.z = cvt_pk_bf16(v1[0], v1[1]); w.w = cvt_pk_bf16(v1[2], v1[3]);
;                     *(u32x4*)(rowp + bj * HALF) = w; } }
;     }
	s_waitcnt lgkmcnt(0)
	s_setprio 1
	s_waitcnt lgkmcnt(0)
	v_mfma_f32_16x16x32_bf16 v[60:63], v[152:155], v[168:171], v[60:63]
	v_mfma_f32_16x16x32_bf16 v[56:59], v[160:163], v[168:171], v[56:59]
	v_mfma_f32_16x16x32_bf16 v[44:47], v[152:155], v[176:179], v[44:47]
	v_mfma_f32_16x16x32_bf16 v[40:43], v[160:163], v[176:179], v[40:43]
	v_mfma_f32_16x16x32_bf16 v[28:31], v[152:155], v[184:187], v[28:31]
	v_mfma_f32_16x16x32_bf16 v[24:27], v[160:163], v[184:187], v[24:27]
	v_mfma_f32_16x16x32_bf16 v[12:15], v[152:155], v[192:195], v[12:15]
	v_mfma_f32_16x16x32_bf16 v[8:11], v[160:163], v[192:195], v[8:11]
	v_mfma_f32_16x16x32_bf16 v[60:63], v[156:159], v[172:175], v[60:63]
	v_mfma_f32_16x16x32_bf16 v[56:59], v[164:167], v[172:175], v[56:59]
	v_mfma_f32_16x16x32_bf16 v[44:47], v[156:159], v[180:183], v[44:47]
	v_mfma_f32_16x16x32_bf16 v[40:43], v[164:167], v[180:183], v[40:43]
	v_mfma_f32_16x16x32_bf16 v[28:31], v[156:159], v[188:191], v[28:31]
	v_mfma_f32_16x16x32_bf16 v[24:27], v[164:167], v[188:191], v[24:27]
	v_mfma_f32_16x16x32_bf16 v[12:15], v[156:159], v[196:199], v[12:15]
	v_mfma_f32_16x16x32_bf16 v[8:11], v[164:167], v[196:199], v[8:11]
	s_setprio 0
	s_barrier
	s_add_u32 s28, s34, 0x80080
	s_addc_u32 s29, s35, 0
	s_add_i32 s34, s84, s42
	s_mov_b32 m0, s34
	s_nop 0
	global_load_lds_dwordx4 v130, s[28:29]
	s_add_i32 m0, s34, 0x2000
	s_nop 0
	global_load_lds_dwordx4 v134, s[28:29]
	s_waitcnt vmcnt(6)
	s_barrier
	s_setprio 1
	v_mfma_f32_16x16x32_bf16 v[52:55], v[202:205], v[168:171], v[52:55]
	v_mfma_f32_16x16x32_bf16 v[48:51], v[210:213], v[168:171], v[48:51]
	v_mfma_f32_16x16x32_bf16 v[36:39], v[202:205], v[176:179], v[36:39]
	v_mfma_f32_16x16x32_bf16 v[32:35], v[210:213], v[176:179], v[32:35]
	v_mfma_f32_16x16x32_bf16 v[20:23], v[202:205], v[184:187], v[20:23]
	v_mfma_f32_16x16x32_bf16 v[16:19], v[210:213], v[184:187], v[16:19]
	v_mfma_f32_16x16x32_bf16 v[4:7], v[202:205], v[192:195], v[4:7]
	v_mfma_f32_16x16x32_bf16 v[0:3], v[210:213], v[192:195], v[0:3]
	v_mfma_f32_16x16x32_bf16 v[52:55], v[206:209], v[172:175], v[52:55]
	v_mfma_f32_16x16x32_bf16 v[48:51], v[214:217], v[172:175], v[48:51]
	v_mfma_f32_16x16x32_bf16 v[36:39], v[206:209], v[180:183], v[36:39]
	v_mfma_f32_16x16x32_bf16 v[32:35], v[214:217], v[180:183], v[32:35]
	v_mfma_f32_16x16x32_bf16 v[20:23], v[206:209], v[188:191], v[20:23]
	v_mfma_f32_16x16x32_bf16 v[16:19], v[214:217], v[188:191], v[16:19]
	v_mfma_f32_16x16x32_bf16 v[4:7], v[206:209], v[196:199], v[4:7]
	v_mfma_f32_16x16x32_bf16 v[0:3], v[214:217], v[196:199], v[0:3]
	s_setprio 0
	s_add_i32 s56, s56, 2
	s_add_u32 s30, s30, 0x100
	s_addc_u32 s31, s31, 0
	s_add_u32 s54, s54, 0x100
	s_addc_u32 s55, s55, 0
	s_cmp_gt_u32 s56, 29
	s_barrier
	s_cbranch_scc0 .LBB0_591
	v_lshl_add_u32 v152, s26, 8, v146
	v_lshl_or_b32 v144, s51, 8, v148
	v_ashrrev_i32_e32 v153, 31, v152
	v_ashrrev_i32_e32 v145, 31, v144
	v_lshlrev_b64 v[154:155], 14, v[152:153]
	v_lshl_add_u64 v[154:155], s[88:89], 0, v[154:155]
	v_lshlrev_b64 v[156:157], 1, v[144:145]
	v_max_f32_e32 v120, 0, v120
	v_max_f32_e32 v121, 0, v121
	v_lshl_add_u64 v[144:145], v[154:155], 0, v[156:157]
	v_pk_mul_f32 v[154:155], v[120:121], v[120:121]
	v_max_f32_e32 v121, v122, v122
	v_max_f32_e32 v120, v126, v126
	v_max_f32_e32 v122, 0, v121
	v_max_f32_e32 v121, v127, v127
	v_max_f32_e32 v124, 0, v124
	v_max_f32_e32 v125, 0, v125
	v_max_f32_e32 v120, 0, v120
	v_max_f32_e32 v121, 0, v121
	v_max_f32_e32 v123, 0, v123
	v_pk_mul_f32 v[124:125], v[124:125], v[124:125]
	v_pk_mul_f32 v[126:127], v[120:121], v[120:121]
	v_pk_mul_f32 v[158:159], v[122:123], v[122:123]
	v_cvt_pk_bf16_f32 v120, v124, v125
	v_cvt_pk_bf16_f32 v121, v126, v127
	v_cvt_pk_bf16_f32 v122, v154, v155
	v_cvt_pk_bf16_f32 v123, v158, v159
	v_max_f32_e32 v112, 0, v112
	v_max_f32_e32 v113, 0, v113
	global_store_dwordx4 v[144:145], v[120:123], off
	s_nop 1
	v_pk_mul_f32 v[120:121], v[112:113], v[112:113]
	v_max_f32_e32 v113, v114, v114
	v_max_f32_e32 v112, v118, v118
	v_max_f32_e32 v114, 0, v113
	v_max_f32_e32 v113, v119, v119
	v_max_f32_e32 v116, 0, v116
	v_max_f32_e32 v117, 0, v117
	v_max_f32_e32 v112, 0, v112
	v_max_f32_e32 v113, 0, v113
	v_max_f32_e32 v115, 0, v115
	v_pk_mul_f32 v[116:117], v[116:117], v[116:117]
	v_pk_mul_f32 v[118:119], v[112:113], v[112:113]
	v_pk_mul_f32 v[122:123], v[114:115], v[114:115]
	v_cvt_pk_bf16_f32 v112, v116, v117
	v_cvt_pk_bf16_f32 v113, v118, v119
	v_cvt_pk_bf16_f32 v114, v120, v121
	v_cvt_pk_bf16_f32 v115, v122, v123
	v_max_f32_e32 v104, 0, v104
	v_max_f32_e32 v105, 0, v105
	global_store_dwordx4 v[144:145], v[112:115], off offset:256
	s_nop 1
	v_or_b32_e32 v112, 16, v152
	v_pk_mul_f32 v[114:115], v[104:105], v[104:105]
	v_max_f32_e32 v105, v106, v106
	v_ashrrev_i32_e32 v113, 31, v112
	v_max_f32_e32 v104, v110, v110
	v_max_f32_e32 v106, 0, v105
	v_max_f32_e32 v105, v111, v111
	v_lshlrev_b64 v[112:113], 14, v[112:113]
	v_max_f32_e32 v108, 0, v108
	v_max_f32_e32 v109, 0, v109
	v_max_f32_e32 v104, 0, v104
	v_max_f32_e32 v105, 0, v105
	v_max_f32_e32 v107, 0, v107
	v_lshl_add_u64 v[112:113], s[88:89], 0, v[112:113]
	v_pk_mul_f32 v[108:109], v[108:109], v[108:109]
	v_pk_mul_f32 v[110:111], v[104:105], v[104:105]
	v_pk_mul_f32 v[116:117], v[106:107], v[106:107]
	v_lshl_add_u64 v[112:113], v[112:113], 0, v[156:157]
	v_cvt_pk_bf16_f32 v104, v108, v109
	v_cvt_pk_bf16_f32 v105, v110, v111
	v_cvt_pk_bf16_f32 v106, v114, v115
	v_cvt_pk_bf16_f32 v107, v116, v117
	v_max_f32_e32 v96, 0, v96
	v_max_f32_e32 v97, 0, v97
	global_store_dwordx4 v[112:113], v[104:107], off
	s_nop 1
	v_pk_mul_f32 v[104:105], v[96:97], v[96:97]
	v_max_f32_e32 v97, v98, v98
	v_max_f32_e32 v96, v102, v102
	v_max_f32_e32 v98, 0, v97
; __device__ __forceinline__ unsigned cvt_pk_bf16(float lo, float hi) { const bf16x2_t r = __builtin_convertvector((f32x2){lo, hi}, bf16x2_t); return __builtin_bit_cast(unsigned, r); }
;     __device__ __forceinline__ void operator()(const AccT& acc, const Unit& u, int wr, int wc, int fr, int fq) const {
;     ...
;             for (int m = 0; m < 4; ++m) { bf16_t* rowp = O + (size_t)(row0 + ai * HALF + m * 16) * DFF + col0;
; #pragma unroll
;                 for (int bj = 0; bj < 2; ++bj) { f32x4 v0 = acc[ai][bj][m][0], v1 = acc[ai][bj][m][1];
; #pragma unroll
;                     for (int j = 0; j < 4; ++j) { float a = fmaxf(v0[j], 0.f), b = fmaxf(v1[j], 0.f); v0[j] = a * a; v1[j] = b * b; }
;                     u32x4 w; w.x = cvt_pk_bf16(v0[0], v0[1]); w.y = cvt_pk_bf16(v0[2], v0[3]); w.z = cvt_pk_bf16(v1[0], v1[1]); w.w = cvt_pk_bf16(v1[2], v1[3]);
;                     *(u32x4*)(rowp + bj * HALF) = w; } }
	v_max_f32_e32 v97, v103, v103
	v_max_f32_e32 v100, 0, v100
	v_max_f32_e32 v101, 0, v101
	v_max_f32_e32 v96, 0, v96
	v_max_f32_e32 v97, 0, v97
	v_max_f32_e32 v99, 0, v99
	v_pk_mul_f32 v[100:101], v[100:101], v[100:101]
	v_pk_mul_f32 v[102:103], v[96:97], v[96:97]
	v_pk_mul_f32 v[106:107], v[98:99], v[98:99]
	v_cvt_pk_bf16_f32 v96, v100, v101
	v_cvt_pk_bf16_f32 v97, v102, v103
	v_cvt_pk_bf16_f32 v98, v104, v105
	v_cvt_pk_bf16_f32 v99, v106, v107
	v_max_f32_e32 v88, 0, v88
	v_max_f32_e32 v89, 0, v89
	global_store_dwordx4 v[112:113], v[96:99], off offset:256
	s_nop 1
	v_or_b32_e32 v96, 32, v152
	v_pk_mul_f32 v[98:99], v[88:89], v[88:89]
	v_max_f32_e32 v89, v90, v90
	v_ashrrev_i32_e32 v97, 31, v96
	v_max_f32_e32 v88, v94, v94
	v_max_f32_e32 v90, 0, v89
	v_max_f32_e32 v89, v95, v95
	v_lshlrev_b64 v[96:97], 14, v[96:97]
	v_max_f32_e32 v92, 0, v92
	v_max_f32_e32 v93, 0, v93
	v_max_f32_e32 v88, 0, v88
	v_max_f32_e32 v89, 0, v89
	v_max_f32_e32 v91, 0, v91
	v_lshl_add_u64 v[96:97], s[88:89], 0, v[96:97]
	v_pk_mul_f32 v[92:93], v[92:93], v[92:93]
	v_pk_mul_f32 v[94:95], v[88:89], v[88:89]
	v_pk_mul_f32 v[100:101], v[90:91], v[90:91]
	v_lshl_add_u64 v[96:97], v[96:97], 0, v[156:157]
	v_cvt_pk_bf16_f32 v88, v92, v93
	v_cvt_pk_bf16_f32 v89, v94, v95
	v_cvt_pk_bf16_f32 v90, v98, v99
	v_cvt_pk_bf16_f32 v91, v100, v101
	v_max_f32_e32 v80, 0, v80
	v_max_f32_e32 v81, 0, v81
	global_store_dwordx4 v[96:97], v[88:91], off
	s_nop 1
	v_pk_mul_f32 v[88:89], v[80:81], v[80:81]
	v_max_f32_e32 v81, v82, v82
	v_max_f32_e32 v80, v86, v86
	v_max_f32_e32 v82, 0, v81
	v_max_f32_e32 v81, v87, v87
	v_max_f32_e32 v84, 0, v84
	v_max_f32_e32 v85, 0, v85
	v_max_f32_e32 v80, 0, v80
	v_max_f32_e32 v81, 0, v81
	v_max_f32_e32 v83, 0, v83
	v_pk_mul_f32 v[84:85], v[84:85], v[84:85]
	v_pk_mul_f32 v[86:87], v[80:81], v[80:81]
	v_pk_mul_f32 v[90:91], v[82:83], v[82:83]
	v_cvt_pk_bf16_f32 v80, v84, v85
	v_cvt_pk_bf16_f32 v81, v86, v87
	v_cvt_pk_bf16_f32 v82, v88, v89
	v_cvt_pk_bf16_f32 v83, v90, v91
	v_max_f32_e32 v72, 0, v72
	v_max_f32_e32 v73, 0, v73
	global_store_dwordx4 v[96:97], v[80:83], off offset:256
	s_nop 1
	v_or_b32_e32 v80, 48, v152
	v_pk_mul_f32 v[82:83], v[72:73], v[72:73]
	v_max_f32_e32 v73, v74, v74
	v_ashrrev_i32_e32 v81, 31, v80
	v_max_f32_e32 v72, v78, v78
	v_max_f32_e32 v74, 0, v73
	v_max_f32_e32 v73, v79, v79
	v_lshlrev_b64 v[80:81], 14, v[80:81]
	v_max_f32_e32 v76, 0, v76
	v_max_f32_e32 v77, 0, v77
	v_max_f32_e32 v72, 0, v72
	v_max_f32_e32 v73, 0, v73
	v_max_f32_e32 v75, 0, v75
	v_lshl_add_u64 v[80:81], s[88:89], 0, v[80:81]
	v_pk_mul_f32 v[76:77], v[76:77], v[76:77]
	v_pk_mul_f32 v[78:79], v[72:73], v[72:73]
	v_pk_mul_f32 v[84:85], v[74:75], v[74:75]
	v_lshl_add_u64 v[80:81], v[80:81], 0, v[156:157]
	v_cvt_pk_bf16_f32 v72, v76, v77
	v_cvt_pk_bf16_f32 v73, v78, v79
	v_cvt_pk_bf16_f32 v74, v82, v83
	v_cvt_pk_bf16_f32 v75, v84, v85
	v_max_f32_e32 v64, 0, v64
	v_max_f32_e32 v65, 0, v65
	global_store_dwordx4 v[80:81], v[72:75], off
	s_nop 1
	v_pk_mul_f32 v[72:73], v[64:65], v[64:65]
	v_max_f32_e32 v65, v66, v66
	v_max_f32_e32 v64, v70, v70
	v_max_f32_e32 v66, 0, v65
	v_max_f32_e32 v65, v71, v71
	v_max_f32_e32 v68, 0, v68
	v_max_f32_e32 v69, 0, v69
	v_max_f32_e32 v64, 0, v64
	v_max_f32_e32 v65, 0, v65
	v_max_f32_e32 v67, 0, v67
	v_pk_mul_f32 v[68:69], v[68:69], v[68:69]
	v_pk_mul_f32 v[70:71], v[64:65], v[64:65]
	v_pk_mul_f32 v[74:75], v[66:67], v[66:67]
	v_cvt_pk_bf16_f32 v64, v68, v69
	v_cvt_pk_bf16_f32 v65, v70, v71
	v_cvt_pk_bf16_f32 v66, v72, v73
	v_cvt_pk_bf16_f32 v67, v74, v75
	v_max_f32_e32 v56, 0, v56
	v_max_f32_e32 v57, 0, v57
	global_store_dwordx4 v[80:81], v[64:67], off offset:256
	s_nop 1
	v_pk_mul_f32 v[66:67], v[56:57], v[56:57]
	v_max_f32_e32 v57, v58, v58
	v_max_f32_e32 v60, 0, v60
	v_max_f32_e32 v61, 0, v61
	v_max_f32_e32 v56, v62, v62
	v_max_f32_e32 v58, 0, v57
	v_max_f32_e32 v57, v63, v63
	v_pk_mul_f32 v[60:61], v[60:61], v[60:61]
	v_max_f32_e32 v56, 0, v56
	v_max_f32_e32 v57, 0, v57
	v_max_f32_e32 v59, 0, v59
	s_mov_b32 s5, 0x200000
	v_pk_mul_f32 v[62:63], v[56:57], v[56:57]
	v_pk_mul_f32 v[68:69], v[58:59], v[58:59]
	v_cvt_pk_bf16_f32 v56, v60, v61
	v_add_co_u32_e32 v60, vcc, s5, v144
	v_cvt_pk_bf16_f32 v57, v62, v63
	v_cvt_pk_bf16_f32 v58, v66, v67
	v_cvt_pk_bf16_f32 v59, v68, v69
	v_addc_co_u32_e32 v61, vcc, 0, v145, vcc
	v_max_f32_e32 v48, 0, v48
	v_max_f32_e32 v49, 0, v49
	global_store_dwordx4 v[60:61], v[56:59], off
	s_nop 1
	v_pk_mul_f32 v[56:57], v[48:49], v[48:49]
	v_max_f32_e32 v49, v50, v50
	v_max_f32_e32 v48, v54, v54
	v_max_f32_e32 v50, 0, v49
	v_max_f32_e32 v49, v55, v55
	v_max_f32_e32 v52, 0, v52
	v_max_f32_e32 v53, 0, v53
	v_max_f32_e32 v48, 0, v48
	v_max_f32_e32 v49, 0, v49
	v_max_f32_e32 v51, 0, v51
	s_mov_b64 s[28:29], 0x200000
	v_pk_mul_f32 v[52:53], v[52:53], v[52:53]
	v_pk_mul_f32 v[54:55], v[48:49], v[48:49]
	v_pk_mul_f32 v[58:59], v[50:51], v[50:51]
	v_lshl_add_u64 v[64:65], v[144:145], 0, s[28:29]
; __device__ __forceinline__ unsigned cvt_pk_bf16(float lo, float hi) { const bf16x2_t r = __builtin_convertvector((f32x2){lo, hi}, bf16x2_t); return __builtin_bit_cast(unsigned, r); }
; #define PG8_WAIT_V(n) asm volatile("s_waitcnt vmcnt(" #n ")" ::: "memory")
; #define PG8_BAR __builtin_amdgcn_s_barrier()
; template <class Epi>
; __device__ __forceinline__ void gemm_phase(LAS unsigned char* lds, const bf16_t* A, int lda, const bf16_t* Bt, int ldb, int M, int N, int K, int asel, const Epi& E, const int fixed_round = -1) {
;     ...
;         if (!has_next) break;
; #pragma unroll
;         for (int a = 0; a < 2; ++a)
; #pragma unroll
;             for (int b = 0; b < 2; ++b)
; #pragma unroll
;                 for (int m = 0; m < 4; ++m)
; #pragma unroll
;                     for (int n = 0; n < 2; ++n) acc[a][b][m][n] = (f32x4){0.f, 0.f, 0.f, 0.f};
;         cur = nxt; cA = nA; cB = nB; ++ui;
;     }
;     PG8_WAIT_V(0);
;     if (wr == 0) PG8_BAR;
;     PG8_BAR;
;     __device__ __forceinline__ void operator()(const AccT& acc, const Unit& u, int wr, int wc, int fr, int fq) const {
;     ...
;             for (int m = 0; m < 4; ++m) { bf16_t* rowp = O + (size_t)(row0 + ai * HALF + m * 16) * DFF + col0;
; #pragma unroll
;                 for (int bj = 0; bj < 2; ++bj) { f32x4 v0 = acc[ai][bj][m][0], v1 = acc[ai][bj][m][1];
; #pragma unroll
;                     for (int j = 0; j < 4; ++j) { float a = fmaxf(v0[j], 0.f), b = fmaxf(v1[j], 0.f); v0[j] = a * a; v1[j] = b * b; }
;                     u32x4 w; w.x = cvt_pk_bf16(v0[0], v0[1]); w.y = cvt_pk_bf16(v0[2], v0[3]); w.z = cvt_pk_bf16(v1[0], v1[1]); w.w = cvt_pk_bf16(v1[2], v1[3]);
;                     *(u32x4*)(rowp + bj * HALF) = w; } }
;     }
	v_cvt_pk_bf16_f32 v48, v52, v53
	v_cvt_pk_bf16_f32 v49, v54, v55
	v_cvt_pk_bf16_f32 v50, v56, v57
	v_cvt_pk_bf16_f32 v51, v58, v59
	v_max_f32_e32 v40, 0, v40
	v_max_f32_e32 v41, 0, v41
	global_store_dwordx4 v[64:65], v[48:51], off offset:256
	s_nop 1
	v_pk_mul_f32 v[50:51], v[40:41], v[40:41]
	v_max_f32_e32 v41, v42, v42
	v_max_f32_e32 v44, 0, v44
	v_max_f32_e32 v45, 0, v45
	v_max_f32_e32 v40, v46, v46
	v_max_f32_e32 v42, 0, v41
	v_max_f32_e32 v41, v47, v47
	v_pk_mul_f32 v[44:45], v[44:45], v[44:45]
	v_max_f32_e32 v40, 0, v40
	v_max_f32_e32 v41, 0, v41
	v_max_f32_e32 v43, 0, v43
	s_mov_b32 s5, 0x240000
	v_pk_mul_f32 v[46:47], v[40:41], v[40:41]
	v_pk_mul_f32 v[52:53], v[42:43], v[42:43]
	v_cvt_pk_bf16_f32 v40, v44, v45
	v_add_co_u32_e32 v44, vcc, s5, v144
	v_cvt_pk_bf16_f32 v41, v46, v47
	v_cvt_pk_bf16_f32 v42, v50, v51
	v_cvt_pk_bf16_f32 v43, v52, v53
	v_addc_co_u32_e32 v45, vcc, 0, v145, vcc
	v_max_f32_e32 v32, 0, v32
	v_max_f32_e32 v33, 0, v33
	global_store_dwordx4 v[44:45], v[40:43], off
	s_nop 1
	v_pk_mul_f32 v[40:41], v[32:33], v[32:33]
	v_max_f32_e32 v33, v34, v34
	v_max_f32_e32 v32, v38, v38
	v_max_f32_e32 v34, 0, v33
	v_max_f32_e32 v33, v39, v39
	v_max_f32_e32 v36, 0, v36
	v_max_f32_e32 v37, 0, v37
	v_max_f32_e32 v32, 0, v32
	v_max_f32_e32 v33, 0, v33
	v_max_f32_e32 v35, 0, v35
	s_mov_b64 s[28:29], 0x240000
	v_pk_mul_f32 v[36:37], v[36:37], v[36:37]
	v_pk_mul_f32 v[38:39], v[32:33], v[32:33]
	v_pk_mul_f32 v[42:43], v[34:35], v[34:35]
	v_lshl_add_u64 v[48:49], v[144:145], 0, s[28:29]
	v_cvt_pk_bf16_f32 v32, v36, v37
	v_cvt_pk_bf16_f32 v33, v38, v39
	v_cvt_pk_bf16_f32 v34, v40, v41
	v_cvt_pk_bf16_f32 v35, v42, v43
	v_max_f32_e32 v24, 0, v24
	v_max_f32_e32 v25, 0, v25
	global_store_dwordx4 v[48:49], v[32:35], off offset:256
	s_nop 1
	v_pk_mul_f32 v[34:35], v[24:25], v[24:25]
	v_max_f32_e32 v25, v26, v26
	v_max_f32_e32 v28, 0, v28
	v_max_f32_e32 v29, 0, v29
	v_max_f32_e32 v24, v30, v30
	v_max_f32_e32 v26, 0, v25
	v_max_f32_e32 v25, v31, v31
	v_pk_mul_f32 v[28:29], v[28:29], v[28:29]
	v_max_f32_e32 v24, 0, v24
	v_max_f32_e32 v25, 0, v25
	v_max_f32_e32 v27, 0, v27
	s_mov_b32 s5, 0x280000
	v_pk_mul_f32 v[30:31], v[24:25], v[24:25]
	v_pk_mul_f32 v[36:37], v[26:27], v[26:27]
	v_cvt_pk_bf16_f32 v24, v28, v29
	v_add_co_u32_e32 v28, vcc, s5, v144
	v_cvt_pk_bf16_f32 v25, v30, v31
	v_cvt_pk_bf16_f32 v26, v34, v35
	v_cvt_pk_bf16_f32 v27, v36, v37
	v_addc_co_u32_e32 v29, vcc, 0, v145, vcc
	v_max_f32_e32 v16, 0, v16
	v_max_f32_e32 v17, 0, v17
	global_store_dwordx4 v[28:29], v[24:27], off
	s_nop 1
	v_pk_mul_f32 v[24:25], v[16:17], v[16:17]
	v_max_f32_e32 v17, v18, v18
	v_max_f32_e32 v16, v22, v22
	v_max_f32_e32 v18, 0, v17
	v_max_f32_e32 v17, v23, v23
	v_max_f32_e32 v20, 0, v20
	v_max_f32_e32 v21, 0, v21
	v_max_f32_e32 v16, 0, v16
	v_max_f32_e32 v17, 0, v17
	v_max_f32_e32 v19, 0, v19
	s_mov_b64 s[28:29], 0x280000
	v_pk_mul_f32 v[20:21], v[20:21], v[20:21]
	v_pk_mul_f32 v[22:23], v[16:17], v[16:17]
	v_pk_mul_f32 v[26:27], v[18:19], v[18:19]
	v_lshl_add_u64 v[32:33], v[144:145], 0, s[28:29]
	v_cvt_pk_bf16_f32 v16, v20, v21
	v_cvt_pk_bf16_f32 v17, v22, v23
	v_cvt_pk_bf16_f32 v18, v24, v25
	v_cvt_pk_bf16_f32 v19, v26, v27
	v_max_f32_e32 v8, 0, v8
	v_max_f32_e32 v9, 0, v9
	global_store_dwordx4 v[32:33], v[16:19], off offset:256
	s_nop 1
	v_pk_mul_f32 v[18:19], v[8:9], v[8:9]
	v_max_f32_e32 v9, v10, v10
	v_max_f32_e32 v12, 0, v12
	v_max_f32_e32 v13, 0, v13
	v_max_f32_e32 v8, v14, v14
	v_max_f32_e32 v10, 0, v9
	v_max_f32_e32 v9, v15, v15
	v_pk_mul_f32 v[12:13], v[12:13], v[12:13]
	v_max_f32_e32 v8, 0, v8
	v_max_f32_e32 v9, 0, v9
	v_max_f32_e32 v11, 0, v11
	v_pk_mul_f32 v[14:15], v[8:9], v[8:9]
	v_pk_mul_f32 v[20:21], v[10:11], v[10:11]
	v_cvt_pk_bf16_f32 v8, v12, v13
	v_add_co_u32_e32 v12, vcc, s50, v144
	v_cvt_pk_bf16_f32 v9, v14, v15
	v_cvt_pk_bf16_f32 v10, v18, v19
	v_cvt_pk_bf16_f32 v11, v20, v21
	v_addc_co_u32_e32 v13, vcc, 0, v145, vcc
	v_max_f32_e32 v0, 0, v0
	v_max_f32_e32 v1, 0, v1
	global_store_dwordx4 v[12:13], v[8:11], off
	s_nop 1
	v_pk_mul_f32 v[8:9], v[0:1], v[0:1]
	v_max_f32_e32 v1, v2, v2
	v_max_f32_e32 v0, v6, v6
	v_max_f32_e32 v2, 0, v1
	v_max_f32_e32 v1, v7, v7
	v_max_f32_e32 v4, 0, v4
	v_max_f32_e32 v5, 0, v5
	v_max_f32_e32 v0, 0, v0
	v_max_f32_e32 v1, 0, v1
	v_max_f32_e32 v3, 0, v3
	s_mov_b64 s[28:29], 0x2c0000
	v_pk_mul_f32 v[4:5], v[4:5], v[4:5]
	v_pk_mul_f32 v[6:7], v[0:1], v[0:1]
	v_pk_mul_f32 v[10:11], v[2:3], v[2:3]
	v_lshl_add_u64 v[16:17], v[144:145], 0, s[28:29]
	v_cvt_pk_bf16_f32 v0, v4, v5
	v_cvt_pk_bf16_f32 v1, v6, v7
	v_cvt_pk_bf16_f32 v2, v8, v9
	v_cvt_pk_bf16_f32 v3, v10, v11
	s_and_b64 vcc, exec, s[0:1]
	s_mov_b32 s51, s4
	s_mov_b32 s26, s6
	s_mov_b64 s[34:35], s[20:21]
	s_mov_b64 s[30:31], s[18:19]
	global_store_dwordx4 v[16:17], v[0:3], off offset:256
	s_cbranch_vccz .LBB0_584
	s_waitcnt vmcnt(0)
	s_cmpk_gt_u32 s33, 0xff
	s_cbranch_scc1 .LBB0_595
	s_barrier

; __device__ __forceinline__ unsigned xb_ld(unsigned* p)              { return __hip_atomic_load(p, __ATOMIC_RELAXED, __HIP_MEMORY_SCOPE_AGENT); }
; __device__ __forceinline__ unsigned xb_add(unsigned* p, unsigned v) { return __hip_atomic_fetch_add(p, v, __ATOMIC_RELAXED, __HIP_MEMORY_SCOPE_AGENT); }
; #define XB_SPIN(cond, bar) do { unsigned _sp = 0; while (cond) { __builtin_amdgcn_s_sleep(1); \
;     if ((++_sp & 255u) == 0u) { if (xb_ld(&(bar)[XB_TMO])) break; if (_sp > XB_SPIN_CAP) { atomicAdd(&(bar)[XB_TMO], 1u); break; } } } } while (0)
; __device__ __forceinline__ void xcd_barrier(const XcdBarrier& b) {
;     ...
;         if (old + 1u == (gen + 1u) * nloc) {
;             __builtin_amdgcn_fence(__ATOMIC_RELEASE, "agent");
;             asm volatile("s_waitcnt vmcnt(0)" ::: "memory");
;             const unsigned og = xb_add(&bar[XB_TOP], 1u);
;             const unsigned tg = og / nx;
;             if (og + 1u == (tg + 1u) * nx) xb_add(&bar[XB_TOPGEN], 1u);
;             else XB_SPIN(xb_ld(&bar[XB_TOPGEN]) == tg, bar);
;             __builtin_amdgcn_fence(__ATOMIC_ACQUIRE, "agent");
;             xb_add(&bar[XB_XGEN(b.x)], 1u);
;             asm volatile("s_waitcnt vmcnt(0)" ::: "memory");
.LBB0_909:
	s_or_b64 exec, exec, s[40:41]
	s_mov_b64 s[40:41], exec
	v_mbcnt_lo_u32_b32 v0, s40, 0
	v_mbcnt_hi_u32_b32 v0, s41, v0
	v_cmp_eq_u32_e32 vcc, 0, v0
	s_waitcnt vmcnt(0)
	s_and_saveexec_b64 s[44:45], vcc
	s_cbranch_execz .LBB0_911
	s_bcnt1_i32_b64 s28, s[40:41]
	v_mov_b32_e32 v0, 0x2000
	v_mov_b32_e32 v1, s28
	global_atomic_add v0, v1, s[4:5] offset:1024
.LBB0_911:
	s_or_b64 exec, exec, s[44:45]
	buffer_inv sc1
	s_waitcnt vmcnt(0)

; __device__ __forceinline__ unsigned xb_ld(unsigned* p)              { return __hip_atomic_load(p, __ATOMIC_RELAXED, __HIP_MEMORY_SCOPE_AGENT); }
; __device__ __forceinline__ unsigned xb_add(unsigned* p, unsigned v) { return __hip_atomic_fetch_add(p, v, __ATOMIC_RELAXED, __HIP_MEMORY_SCOPE_AGENT); }
; #define XB_SPIN(cond, bar) do { unsigned _sp = 0; while (cond) { __builtin_amdgcn_s_sleep(1); \
;     if ((++_sp & 255u) == 0u) { if (xb_ld(&(bar)[XB_TMO])) break; if (_sp > XB_SPIN_CAP) { atomicAdd(&(bar)[XB_TMO], 1u); break; } } } } while (0)
; __device__ __forceinline__ void xcd_barrier(const XcdBarrier& b) {
;     ...
;         if (old + 1u == (gen + 1u) * nloc) {
;             __builtin_amdgcn_fence(__ATOMIC_RELEASE, "agent");
;             asm volatile("s_waitcnt vmcnt(0)" ::: "memory");
;             const unsigned og = xb_add(&bar[XB_TOP], 1u);
;             const unsigned tg = og / nx;
;             if (og + 1u == (tg + 1u) * nx) xb_add(&bar[XB_TOPGEN], 1u);
;             else XB_SPIN(xb_ld(&bar[XB_TOPGEN]) == tg, bar);
;             __builtin_amdgcn_fence(__ATOMIC_ACQUIRE, "agent");
;             xb_add(&bar[XB_XGEN(b.x)], 1u);
;             asm volatile("s_waitcnt vmcnt(0)" ::: "memory");
.LBB0_1011:
	s_or_b64 exec, exec, s[40:41]
	s_mov_b64 s[40:41], exec
	v_mbcnt_lo_u32_b32 v0, s40, 0
	v_mbcnt_hi_u32_b32 v0, s41, v0
	v_cmp_eq_u32_e32 vcc, 0, v0
	s_waitcnt vmcnt(0)
	s_and_saveexec_b64 s[42:43], vcc
	s_cbranch_execz .LBB0_1013
	s_bcnt1_i32_b64 s28, s[40:41]
	v_mov_b32_e32 v0, 0x2000
	v_mov_b32_e32 v1, s28
	global_atomic_add v0, v1, s[4:5] offset:1024
.LBB0_1013:
	s_or_b64 exec, exec, s[42:43]
	buffer_inv sc1
	s_waitcnt vmcnt(0)

; __device__ __forceinline__ unsigned xb_ld(unsigned* p)              { return __hip_atomic_load(p, __ATOMIC_RELAXED, __HIP_MEMORY_SCOPE_AGENT); }
; __device__ __forceinline__ unsigned xb_add(unsigned* p, unsigned v) { return __hip_atomic_fetch_add(p, v, __ATOMIC_RELAXED, __HIP_MEMORY_SCOPE_AGENT); }
; #define XB_SPIN(cond, bar) do { unsigned _sp = 0; while (cond) { __builtin_amdgcn_s_sleep(1); \
;     if ((++_sp & 255u) == 0u) { if (xb_ld(&(bar)[XB_TMO])) break; if (_sp > XB_SPIN_CAP) { atomicAdd(&(bar)[XB_TMO], 1u); break; } } } } while (0)
; __device__ __forceinline__ void xcd_barrier(const XcdBarrier& b) {
;     ...
;         if (old + 1u == (gen + 1u) * nloc) {
;             __builtin_amdgcn_fence(__ATOMIC_RELEASE, "agent");
;             asm volatile("s_waitcnt vmcnt(0)" ::: "memory");
;             const unsigned og = xb_add(&bar[XB_TOP], 1u);
;             const unsigned tg = og / nx;
;             if (og + 1u == (tg + 1u) * nx) xb_add(&bar[XB_TOPGEN], 1u);
;             else XB_SPIN(xb_ld(&bar[XB_TOPGEN]) == tg, bar);
;             __builtin_amdgcn_fence(__ATOMIC_ACQUIRE, "agent");
;             xb_add(&bar[XB_XGEN(b.x)], 1u);
;             asm volatile("s_waitcnt vmcnt(0)" ::: "memory");
.LBB0_1075:
	s_or_b64 exec, exec, s[4:5]
	s_mov_b64 s[4:5], exec
	v_mbcnt_lo_u32_b32 v0, s4, 0
	v_mbcnt_hi_u32_b32 v0, s5, v0
	v_cmp_eq_u32_e32 vcc, 0, v0
	s_waitcnt vmcnt(0)
	s_and_saveexec_b64 s[40:41], vcc
	s_cbranch_execz .LBB0_1077
	s_bcnt1_i32_b64 s4, s[4:5]
	v_mov_b32_e32 v0, 0x2000
	v_mov_b32_e32 v1, s4
	global_atomic_add v0, v1, s[2:3] offset:1024
.LBB0_1077:
	s_or_b64 exec, exec, s[40:41]
	buffer_inv sc1
	s_waitcnt vmcnt(0)

; #define PG8_STAGE(bufoff, gbase, voff) do { _Pragma("unroll") for (int _i = 0; _i < 2; ++_i) \
;         __builtin_amdgcn_global_load_lds((const unsigned*)((const char*)(gbase) + (voff)[_i]), (LAS unsigned*)(lds + (bufoff) + ldsw + _i * 8192), 16, 0, 0); } while (0)
; #define PG8_LDA(dst, b, h) do { _Pragma("unroll") for (int m = 0; m < 4; ++m) _Pragma("unroll") for (int k = 0; k < 2; ++k) dst[m][k] = *(const LAS bf16x8*)(lds + PG8_SA(b, h) + aoff + m * 2048 + k * 1024); } while (0)
; #define PG8_LDB(dst, b, h) do { _Pragma("unroll") for (int n = 0; n < 2; ++n) _Pragma("unroll") for (int k = 0; k < 2; ++k) dst[n][k] = *(const LAS bf16x8*)(lds + PG8_SB(b, h) + boff + n * 2048 + k * 1024); } while (0)
; #define PG8_WAIT_V(n) asm volatile("s_waitcnt vmcnt(" #n ")" ::: "memory")
; #define PG8_WAIT_L(n) asm volatile("s_waitcnt lgkmcnt(" #n ")" ::: "memory")
; #define PG8_BAR __builtin_amdgcn_s_barrier()
; #define PG8_SCHED __builtin_amdgcn_sched_barrier(0)
; template <class Epi>
; __device__ __forceinline__ void gemm_phase(LAS unsigned char* lds, const bf16_t* A, int lda, const bf16_t* Bt, int ldb, int M, int N, int K, int asel, const Epi& E, const int fixed_round = -1) {
;     ...
;         for (int t = 0; t < nt; t += 2) {
;             const bool last = (t == nt - 2);
;             const char* a1 = cA + (size_t)(t + 1) * kstep;
;             const char* a2 = last ? nA : cA + (size_t)(t + 2) * kstep; const char* b2 = last ? nB : cB + (size_t)(t + 2) * kstep;
;             const char* a3 = a2 + kstep; const char* b3 = b2 + kstep;
;             PG8_LDB(B0, 0, 0); PG8_SCHED; PG8_LDA(At, 0, 0); PG8_STAGE(PG8_SA(1, 1), a1 + hstepA, voffA);
;             PG8_WAIT_L(8); PG8_BAR; PG8_WAIT_L(0); PG8_MMA(0, 0, At, B0); PG8_BAR; PG8_SCHED;
;             PG8_LDB(B1, 0, 1); PG8_STAGE(PG8_SB(0, 0), b2, voffB);
;             PG8_BAR; PG8_WAIT_L(0); PG8_MMA(0, 1, At, B1); PG8_BAR;
;             PG8_LDA(At, 0, 1); PG8_STAGE(PG8_SA(0, 0), a2, voffA);
;             PG8_BAR; PG8_WAIT_L(0); PG8_MMA(1, 0, At, B0); PG8_BAR; PG8_SCHED;
;             PG8_STAGE(PG8_SB(0, 1), b2 + hstepB, voffB);
;             PG8_WAIT_V(6); PG8_BAR; PG8_MMA(1, 1, At, B1); PG8_BAR;
.LBB0_1223:
	ds_read_b128 v[152:155], v149
	ds_read_b128 v[156:159], v149 offset:1024
	ds_read_b128 v[160:163], v149 offset:2048
	ds_read_b128 v[164:167], v149 offset:3072
	s_add_u32 s48, s46, 0xfff80080
	s_addc_u32 s49, s47, -1
	s_cmp_eq_u32 s70, 28
	s_cselect_b32 s51, s29, s49
	s_cselect_b32 s50, s66, s48
	s_cselect_b32 s49, s25, s69
	s_cselect_b32 s48, s67, s68
	s_add_i32 m0, s45, 0xc000
	ds_read_b128 v[168:171], v150
	ds_read_b128 v[172:175], v150 offset:1024
	ds_read_b128 v[176:179], v150 offset:2048
	ds_read_b128 v[180:183], v150 offset:3072
	ds_read_b128 v[184:187], v150 offset:4096
	ds_read_b128 v[188:191], v150 offset:5120
	ds_read_b128 v[192:195], v150 offset:6144
	ds_read_b128 v[196:199], v150 offset:7168
	global_load_lds_dwordx4 v136, s[46:47]
	s_add_i32 m0, s45, 0xe000
	s_nop 0
	global_load_lds_dwordx4 v138, s[46:47]
	s_waitcnt lgkmcnt(8)
	s_barrier
	s_waitcnt lgkmcnt(0)
	s_setprio 1
	s_waitcnt lgkmcnt(0)
	v_mfma_f32_16x16x32_bf16 v[124:127], v[152:155], v[168:171], v[124:127]
	v_mfma_f32_16x16x32_bf16 v[120:123], v[160:163], v[168:171], v[120:123]
	v_mfma_f32_16x16x32_bf16 v[108:111], v[152:155], v[176:179], v[108:111]
	v_mfma_f32_16x16x32_bf16 v[104:107], v[160:163], v[176:179], v[104:107]
	v_mfma_f32_16x16x32_bf16 v[92:95], v[152:155], v[184:187], v[92:95]
	v_mfma_f32_16x16x32_bf16 v[88:91], v[160:163], v[184:187], v[88:91]
	v_mfma_f32_16x16x32_bf16 v[76:79], v[152:155], v[192:195], v[76:79]
	v_mfma_f32_16x16x32_bf16 v[72:75], v[160:163], v[192:195], v[72:75]
	v_mfma_f32_16x16x32_bf16 v[124:127], v[156:159], v[172:175], v[124:127]
	v_mfma_f32_16x16x32_bf16 v[120:123], v[164:167], v[172:175], v[120:123]
	v_mfma_f32_16x16x32_bf16 v[108:111], v[156:159], v[180:183], v[108:111]
	v_mfma_f32_16x16x32_bf16 v[104:107], v[164:167], v[180:183], v[104:107]
	v_mfma_f32_16x16x32_bf16 v[92:95], v[156:159], v[188:191], v[92:95]
	v_mfma_f32_16x16x32_bf16 v[88:91], v[164:167], v[188:191], v[88:91]
	v_mfma_f32_16x16x32_bf16 v[76:79], v[156:159], v[196:199], v[76:79]
	v_mfma_f32_16x16x32_bf16 v[72:75], v[164:167], v[196:199], v[72:75]
	s_setprio 0
	s_barrier
	s_add_i32 s71, s81, s54
	s_add_u32 s98, s48, s2
	s_addc_u32 s99, s49, s3
	s_mov_b32 m0, s71
	ds_read_b128 v[202:205], v151
	ds_read_b128 v[206:209], v151 offset:1024
	ds_read_b128 v[210:213], v151 offset:2048
	ds_read_b128 v[214:217], v151 offset:3072
	global_load_lds_dwordx4 v130, s[48:49]
	s_add_i32 m0, s71, 0x2000
	s_nop 0
	global_load_lds_dwordx4 v134, s[48:49]
	s_barrier
	s_waitcnt lgkmcnt(0)
	s_setprio 1
	s_waitcnt lgkmcnt(0)
	v_mfma_f32_16x16x32_bf16 v[116:119], v[202:205], v[168:171], v[116:119]
	v_mfma_f32_16x16x32_bf16 v[112:115], v[210:213], v[168:171], v[112:115]
	v_mfma_f32_16x16x32_bf16 v[100:103], v[202:205], v[176:179], v[100:103]
	v_mfma_f32_16x16x32_bf16 v[96:99], v[210:213], v[176:179], v[96:99]
	v_mfma_f32_16x16x32_bf16 v[84:87], v[202:205], v[184:187], v[84:87]
	v_mfma_f32_16x16x32_bf16 v[80:83], v[210:213], v[184:187], v[80:83]
	v_mfma_f32_16x16x32_bf16 v[68:71], v[202:205], v[192:195], v[68:71]
	v_mfma_f32_16x16x32_bf16 v[64:67], v[210:213], v[192:195], v[64:67]
	v_mfma_f32_16x16x32_bf16 v[116:119], v[206:209], v[172:175], v[116:119]
	v_mfma_f32_16x16x32_bf16 v[112:115], v[214:217], v[172:175], v[112:115]
	v_mfma_f32_16x16x32_bf16 v[100:103], v[206:209], v[180:183], v[100:103]
	v_mfma_f32_16x16x32_bf16 v[96:99], v[214:217], v[180:183], v[96:99]
	v_mfma_f32_16x16x32_bf16 v[84:87], v[206:209], v[188:191], v[84:87]
	v_mfma_f32_16x16x32_bf16 v[80:83], v[214:217], v[188:191], v[80:83]
	v_mfma_f32_16x16x32_bf16 v[68:71], v[206:209], v[196:199], v[68:71]
	v_mfma_f32_16x16x32_bf16 v[64:67], v[214:217], v[196:199], v[64:67]
	s_setprio 0
	s_mov_b32 m0, s45
	s_add_u32 s100, s50, s2
	s_addc_u32 s101, s51, s3
	s_barrier
	ds_read_b128 v[168:171], v150 offset:16384
	ds_read_b128 v[172:175], v150 offset:17408
	ds_read_b128 v[176:179], v150 offset:18432
	ds_read_b128 v[180:183], v150 offset:19456
	ds_read_b128 v[184:187], v150 offset:20480
	ds_read_b128 v[188:191], v150 offset:21504
	ds_read_b128 v[192:195], v150 offset:22528
	ds_read_b128 v[196:199], v150 offset:23552
	global_load_lds_dwordx4 v128, s[50:51]
	s_mov_b32 m0, s55
	s_nop 0
	global_load_lds_dwordx4 v132, s[50:51]
	s_barrier
	s_waitcnt lgkmcnt(0)
	s_setprio 1
	s_waitcnt lgkmcnt(0)
	v_mfma_f32_16x16x32_bf16 v[60:63], v[152:155], v[168:171], v[60:63]
	v_mfma_f32_16x16x32_bf16 v[56:59], v[160:163], v[168:171], v[56:59]
	v_mfma_f32_16x16x32_bf16 v[44:47], v[152:155], v[176:179], v[44:47]
	v_mfma_f32_16x16x32_bf16 v[40:43], v[160:163], v[176:179], v[40:43]
	v_mfma_f32_16x16x32_bf16 v[28:31], v[152:155], v[184:187], v[28:31]
	v_mfma_f32_16x16x32_bf16 v[24:27], v[160:163], v[184:187], v[24:27]
	v_mfma_f32_16x16x32_bf16 v[12:15], v[152:155], v[192:195], v[12:15]
	v_mfma_f32_16x16x32_bf16 v[8:11], v[160:163], v[192:195], v[8:11]
	v_mfma_f32_16x16x32_bf16 v[60:63], v[156:159], v[172:175], v[60:63]
	v_mfma_f32_16x16x32_bf16 v[56:59], v[164:167], v[172:175], v[56:59]
	v_mfma_f32_16x16x32_bf16 v[44:47], v[156:159], v[180:183], v[44:47]
	v_mfma_f32_16x16x32_bf16 v[40:43], v[164:167], v[180:183], v[40:43]
	v_mfma_f32_16x16x32_bf16 v[28:31], v[156:159], v[188:191], v[28:31]
	v_mfma_f32_16x16x32_bf16 v[24:27], v[164:167], v[188:191], v[24:27]
	v_mfma_f32_16x16x32_bf16 v[12:15], v[156:159], v[196:199], v[12:15]
	v_mfma_f32_16x16x32_bf16 v[8:11], v[164:167], v[196:199], v[8:11]
	s_setprio 0
	s_barrier
	s_add_u32 s72, s48, 0x80000
	s_addc_u32 s73, s49, 0
	s_add_i32 s71, s82, s54
	s_mov_b32 m0, s71
	s_nop 0
	global_load_lds_dwordx4 v130, s[72:73]
	s_add_i32 m0, s71, 0x2000
	s_nop 0
	global_load_lds_dwordx4 v134, s[72:73]
	s_waitcnt vmcnt(6)
	s_barrier
; #define PG8_STAGE(bufoff, gbase, voff) do { _Pragma("unroll") for (int _i = 0; _i < 2; ++_i) \
;         __builtin_amdgcn_global_load_lds((const unsigned*)((const char*)(gbase) + (voff)[_i]), (LAS unsigned*)(lds + (bufoff) + ldsw + _i * 8192), 16, 0, 0); } while (0)
; #define PG8_LDA(dst, b, h) do { _Pragma("unroll") for (int m = 0; m < 4; ++m) _Pragma("unroll") for (int k = 0; k < 2; ++k) dst[m][k] = *(const LAS bf16x8*)(lds + PG8_SA(b, h) + aoff + m * 2048 + k * 1024); } while (0)
; #define PG8_LDB(dst, b, h) do { _Pragma("unroll") for (int n = 0; n < 2; ++n) _Pragma("unroll") for (int k = 0; k < 2; ++k) dst[n][k] = *(const LAS bf16x8*)(lds + PG8_SB(b, h) + boff + n * 2048 + k * 1024); } while (0)
; #define PG8_WAIT_V(n) asm volatile("s_waitcnt vmcnt(" #n ")" ::: "memory")
; #define PG8_WAIT_L(n) asm volatile("s_waitcnt lgkmcnt(" #n ")" ::: "memory")
; #define PG8_BAR __builtin_amdgcn_s_barrier()
; #define PG8_SCHED __builtin_amdgcn_sched_barrier(0)
; template <class Epi>
; __device__ __forceinline__ void gemm_phase(LAS unsigned char* lds, const bf16_t* A, int lda, const bf16_t* Bt, int ldb, int M, int N, int K, int asel, const Epi& E, const int fixed_round = -1) {
;     ...
;             PG8_STAGE(PG8_SB(0, 1), b2 + hstepB, voffB);
;             PG8_WAIT_V(6); PG8_BAR; PG8_MMA(1, 1, At, B1); PG8_BAR;
;             PG8_LDB(B0, 1, 0); PG8_SCHED; PG8_LDA(At, 1, 0); PG8_STAGE(PG8_SA(0, 1), a2 + hstepA, voffA);
;             PG8_WAIT_L(8); PG8_BAR; PG8_WAIT_L(0); PG8_MMA(0, 0, At, B0); PG8_BAR; PG8_SCHED;
;             PG8_LDB(B1, 1, 1); PG8_STAGE(PG8_SB(1, 0), b3, voffB);
;             PG8_BAR; PG8_WAIT_L(0); PG8_MMA(0, 1, At, B1); PG8_BAR;
;             PG8_LDA(At, 1, 1); PG8_STAGE(PG8_SA(1, 0), a3, voffA);
;             PG8_BAR; PG8_WAIT_L(0); PG8_MMA(1, 0, At, B0); PG8_BAR; PG8_SCHED;
	s_setprio 1
	v_mfma_f32_16x16x32_bf16 v[52:55], v[202:205], v[168:171], v[52:55]
	v_mfma_f32_16x16x32_bf16 v[48:51], v[210:213], v[168:171], v[48:51]
	v_mfma_f32_16x16x32_bf16 v[36:39], v[202:205], v[176:179], v[36:39]
	v_mfma_f32_16x16x32_bf16 v[32:35], v[210:213], v[176:179], v[32:35]
	v_mfma_f32_16x16x32_bf16 v[20:23], v[202:205], v[184:187], v[20:23]
	v_mfma_f32_16x16x32_bf16 v[16:19], v[210:213], v[184:187], v[16:19]
	v_mfma_f32_16x16x32_bf16 v[4:7], v[202:205], v[192:195], v[4:7]
	v_mfma_f32_16x16x32_bf16 v[0:3], v[210:213], v[192:195], v[0:3]
	v_mfma_f32_16x16x32_bf16 v[52:55], v[206:209], v[172:175], v[52:55]
	v_mfma_f32_16x16x32_bf16 v[48:51], v[214:217], v[172:175], v[48:51]
	v_mfma_f32_16x16x32_bf16 v[36:39], v[206:209], v[180:183], v[36:39]
	v_mfma_f32_16x16x32_bf16 v[32:35], v[214:217], v[180:183], v[32:35]
	v_mfma_f32_16x16x32_bf16 v[20:23], v[206:209], v[188:191], v[20:23]
	v_mfma_f32_16x16x32_bf16 v[16:19], v[214:217], v[188:191], v[16:19]
	v_mfma_f32_16x16x32_bf16 v[4:7], v[206:209], v[196:199], v[4:7]
	v_mfma_f32_16x16x32_bf16 v[0:3], v[214:217], v[196:199], v[0:3]
	s_setprio 0
	v_add_u32_e32 v164, s83, v147
	s_barrier
	ds_read_b128 v[152:155], v164
	ds_read_b128 v[156:159], v164 offset:1024
	ds_read_b128 v[160:163], v164 offset:2048
	ds_read_b128 v[164:167], v164 offset:3072
	s_add_u32 s50, s50, 0x80000
	s_addc_u32 s51, s51, 0
	s_mov_b32 m0, s56
	ds_read_b128 v[168:171], v150 offset:32768
	ds_read_b128 v[172:175], v150 offset:33792
	ds_read_b128 v[176:179], v150 offset:34816
	ds_read_b128 v[180:183], v150 offset:35840
	ds_read_b128 v[184:187], v150 offset:36864
	ds_read_b128 v[188:191], v150 offset:37888
	ds_read_b128 v[192:195], v150 offset:38912
	ds_read_b128 v[196:199], v150 offset:39936
	global_load_lds_dwordx4 v128, s[50:51]
	s_mov_b32 m0, s57
	s_nop 0
	global_load_lds_dwordx4 v132, s[50:51]
	s_waitcnt lgkmcnt(8)
	s_barrier
	s_waitcnt lgkmcnt(0)
	s_setprio 1
	s_waitcnt lgkmcnt(0)
	v_mfma_f32_16x16x32_bf16 v[124:127], v[152:155], v[168:171], v[124:127]
	v_mfma_f32_16x16x32_bf16 v[120:123], v[160:163], v[168:171], v[120:123]
	v_mfma_f32_16x16x32_bf16 v[108:111], v[152:155], v[176:179], v[108:111]
	v_mfma_f32_16x16x32_bf16 v[104:107], v[160:163], v[176:179], v[104:107]
	v_mfma_f32_16x16x32_bf16 v[92:95], v[152:155], v[184:187], v[92:95]
	v_mfma_f32_16x16x32_bf16 v[88:91], v[160:163], v[184:187], v[88:91]
	v_mfma_f32_16x16x32_bf16 v[76:79], v[152:155], v[192:195], v[76:79]
	v_mfma_f32_16x16x32_bf16 v[72:75], v[160:163], v[192:195], v[72:75]
	v_mfma_f32_16x16x32_bf16 v[124:127], v[156:159], v[172:175], v[124:127]
	v_mfma_f32_16x16x32_bf16 v[120:123], v[164:167], v[172:175], v[120:123]
	v_mfma_f32_16x16x32_bf16 v[108:111], v[156:159], v[180:183], v[108:111]
	v_mfma_f32_16x16x32_bf16 v[104:107], v[164:167], v[180:183], v[104:107]
	v_mfma_f32_16x16x32_bf16 v[92:95], v[156:159], v[188:191], v[92:95]
	v_mfma_f32_16x16x32_bf16 v[88:91], v[164:167], v[188:191], v[88:91]
	v_mfma_f32_16x16x32_bf16 v[76:79], v[156:159], v[196:199], v[76:79]
	v_mfma_f32_16x16x32_bf16 v[72:75], v[164:167], v[196:199], v[72:75]
	s_setprio 0
	s_barrier
	s_add_i32 s50, s83, s54
	v_add_u32_e32 v214, s84, v147
	s_mov_b32 m0, s50
	ds_read_b128 v[202:205], v214
	ds_read_b128 v[206:209], v214 offset:1024
	ds_read_b128 v[210:213], v214 offset:2048
	ds_read_b128 v[214:217], v214 offset:3072
	global_load_lds_dwordx4 v130, s[98:99]
	s_add_i32 m0, s50, 0x2000
	s_nop 0
	global_load_lds_dwordx4 v134, s[98:99]
	s_barrier
	s_waitcnt lgkmcnt(0)
	s_setprio 1
	s_waitcnt lgkmcnt(0)
	v_mfma_f32_16x16x32_bf16 v[116:119], v[202:205], v[168:171], v[116:119]
	v_mfma_f32_16x16x32_bf16 v[112:115], v[210:213], v[168:171], v[112:115]
	v_mfma_f32_16x16x32_bf16 v[100:103], v[202:205], v[176:179], v[100:103]
	v_mfma_f32_16x16x32_bf16 v[96:99], v[210:213], v[176:179], v[96:99]
	v_mfma_f32_16x16x32_bf16 v[84:87], v[202:205], v[184:187], v[84:87]
	v_mfma_f32_16x16x32_bf16 v[80:83], v[210:213], v[184:187], v[80:83]
	v_mfma_f32_16x16x32_bf16 v[68:71], v[202:205], v[192:195], v[68:71]
	v_mfma_f32_16x16x32_bf16 v[64:67], v[210:213], v[192:195], v[64:67]
	v_mfma_f32_16x16x32_bf16 v[116:119], v[206:209], v[172:175], v[116:119]
	v_mfma_f32_16x16x32_bf16 v[112:115], v[214:217], v[172:175], v[112:115]
	v_mfma_f32_16x16x32_bf16 v[100:103], v[206:209], v[180:183], v[100:103]
	v_mfma_f32_16x16x32_bf16 v[96:99], v[214:217], v[180:183], v[96:99]
	v_mfma_f32_16x16x32_bf16 v[84:87], v[206:209], v[188:191], v[84:87]
	v_mfma_f32_16x16x32_bf16 v[80:83], v[214:217], v[188:191], v[80:83]
	v_mfma_f32_16x16x32_bf16 v[68:71], v[206:209], v[196:199], v[68:71]
	v_mfma_f32_16x16x32_bf16 v[64:67], v[214:217], v[196:199], v[64:67]
	s_setprio 0
	s_mov_b32 m0, s59
	s_barrier
	ds_read_b128 v[168:171], v150 offset:49152
	ds_read_b128 v[172:175], v150 offset:50176
	ds_read_b128 v[176:179], v150 offset:51200
	ds_read_b128 v[180:183], v150 offset:52224
	ds_read_b128 v[184:187], v150 offset:53248
	ds_read_b128 v[188:191], v150 offset:54272
	ds_read_b128 v[192:195], v150 offset:55296
	ds_read_b128 v[196:199], v150 offset:56320
	global_load_lds_dwordx4 v128, s[100:101]
	s_mov_b32 m0, s60
	s_nop 0
	global_load_lds_dwordx4 v132, s[100:101]
	s_barrier
; __device__ __forceinline__ unsigned cvt_pk_bf16(float lo, float hi) { const bf16x2_t r = __builtin_convertvector((f32x2){lo, hi}, bf16x2_t); return __builtin_bit_cast(unsigned, r); }
; #define PG8_STAGE(bufoff, gbase, voff) do { _Pragma("unroll") for (int _i = 0; _i < 2; ++_i) \
;         __builtin_amdgcn_global_load_lds((const unsigned*)((const char*)(gbase) + (voff)[_i]), (LAS unsigned*)(lds + (bufoff) + ldsw + _i * 8192), 16, 0, 0); } while (0)
; #define PG8_WAIT_V(n) asm volatile("s_waitcnt vmcnt(" #n ")" ::: "memory")
; #define PG8_WAIT_L(n) asm volatile("s_waitcnt lgkmcnt(" #n ")" ::: "memory")
; #define PG8_BAR __builtin_amdgcn_s_barrier()
; #define PG8_SCHED __builtin_amdgcn_sched_barrier(0)
; template <class Epi>
; __device__ __forceinline__ void gemm_phase(LAS unsigned char* lds, const bf16_t* A, int lda, const bf16_t* Bt, int ldb, int M, int N, int K, int asel, const Epi& E, const int fixed_round = -1) {
;     ...
;             PG8_BAR; PG8_WAIT_L(0); PG8_MMA(1, 0, At, B0); PG8_BAR; PG8_SCHED;
;             PG8_STAGE(PG8_SB(1, 1), b3 + hstepB, voffB);
;             PG8_WAIT_V(6); PG8_BAR; PG8_MMA(1, 1, At, B1); PG8_BAR;
;     __device__ __forceinline__ void operator()(const AccT& acc, const Unit& u, int wr, int wc, int fr, int fq) const {
;         const int row0 = u.pm * BM + wr * 64 + fr, col0 = u.pn * BM + wc * 32 + 8 * fq;
; #pragma unroll
;         for (int ai = 0; ai < 2; ++ai)
; #pragma unroll
;             for (int m = 0; m < 4; ++m) { bf16_t* rowp = O + (size_t)(row0 + ai * HALF + m * 16) * DFF + col0;
; #pragma unroll
;                 for (int bj = 0; bj < 2; ++bj) { f32x4 v0 = acc[ai][bj][m][0], v1 = acc[ai][bj][m][1];
; #pragma unroll
;                     for (int j = 0; j < 4; ++j) { float a = fmaxf(v0[j], 0.f), b = fmaxf(v1[j], 0.f); v0[j] = a * a; v1[j] = b * b; }
;                     u32x4 w; w.x = cvt_pk_bf16(v0[0], v0[1]); w.y = cvt_pk_bf16(v0[2], v0[3]); w.z = cvt_pk_bf16(v1[0], v1[1]); w.w = cvt_pk_bf16(v1[2], v1[3]);
;                     *(u32x4*)(rowp + bj * HALF) = w; } }
;     }
	s_waitcnt lgkmcnt(0)
	s_setprio 1
	s_waitcnt lgkmcnt(0)
	v_mfma_f32_16x16x32_bf16 v[60:63], v[152:155], v[168:171], v[60:63]
	v_mfma_f32_16x16x32_bf16 v[56:59], v[160:163], v[168:171], v[56:59]
	v_mfma_f32_16x16x32_bf16 v[44:47], v[152:155], v[176:179], v[44:47]
	v_mfma_f32_16x16x32_bf16 v[40:43], v[160:163], v[176:179], v[40:43]
	v_mfma_f32_16x16x32_bf16 v[28:31], v[152:155], v[184:187], v[28:31]
	v_mfma_f32_16x16x32_bf16 v[24:27], v[160:163], v[184:187], v[24:27]
	v_mfma_f32_16x16x32_bf16 v[12:15], v[152:155], v[192:195], v[12:15]
	v_mfma_f32_16x16x32_bf16 v[8:11], v[160:163], v[192:195], v[8:11]
	v_mfma_f32_16x16x32_bf16 v[60:63], v[156:159], v[172:175], v[60:63]
	v_mfma_f32_16x16x32_bf16 v[56:59], v[164:167], v[172:175], v[56:59]
	v_mfma_f32_16x16x32_bf16 v[44:47], v[156:159], v[180:183], v[44:47]
	v_mfma_f32_16x16x32_bf16 v[40:43], v[164:167], v[180:183], v[40:43]
	v_mfma_f32_16x16x32_bf16 v[28:31], v[156:159], v[188:191], v[28:31]
	v_mfma_f32_16x16x32_bf16 v[24:27], v[164:167], v[188:191], v[24:27]
	v_mfma_f32_16x16x32_bf16 v[12:15], v[156:159], v[196:199], v[12:15]
	v_mfma_f32_16x16x32_bf16 v[8:11], v[164:167], v[196:199], v[8:11]
	s_setprio 0
	s_barrier
	s_add_u32 s48, s48, 0x80080
	s_addc_u32 s49, s49, 0
	s_add_i32 s50, s84, s54
	s_mov_b32 m0, s50
	s_nop 0
	global_load_lds_dwordx4 v130, s[48:49]
	s_add_i32 m0, s50, 0x2000
	s_nop 0
	global_load_lds_dwordx4 v134, s[48:49]
	s_waitcnt vmcnt(6)
	s_barrier
	s_setprio 1
	v_mfma_f32_16x16x32_bf16 v[52:55], v[202:205], v[168:171], v[52:55]
	v_mfma_f32_16x16x32_bf16 v[48:51], v[210:213], v[168:171], v[48:51]
	v_mfma_f32_16x16x32_bf16 v[36:39], v[202:205], v[176:179], v[36:39]
	v_mfma_f32_16x16x32_bf16 v[32:35], v[210:213], v[176:179], v[32:35]
	v_mfma_f32_16x16x32_bf16 v[20:23], v[202:205], v[184:187], v[20:23]
	v_mfma_f32_16x16x32_bf16 v[16:19], v[210:213], v[184:187], v[16:19]
	v_mfma_f32_16x16x32_bf16 v[4:7], v[202:205], v[192:195], v[4:7]
	v_mfma_f32_16x16x32_bf16 v[0:3], v[210:213], v[192:195], v[0:3]
	v_mfma_f32_16x16x32_bf16 v[52:55], v[206:209], v[172:175], v[52:55]
	v_mfma_f32_16x16x32_bf16 v[48:51], v[214:217], v[172:175], v[48:51]
	v_mfma_f32_16x16x32_bf16 v[36:39], v[206:209], v[180:183], v[36:39]
	v_mfma_f32_16x16x32_bf16 v[32:35], v[214:217], v[180:183], v[32:35]
	v_mfma_f32_16x16x32_bf16 v[20:23], v[206:209], v[188:191], v[20:23]
	v_mfma_f32_16x16x32_bf16 v[16:19], v[214:217], v[188:191], v[16:19]
	v_mfma_f32_16x16x32_bf16 v[4:7], v[206:209], v[196:199], v[4:7]
	v_mfma_f32_16x16x32_bf16 v[0:3], v[214:217], v[196:199], v[0:3]
	s_setprio 0
	s_add_i32 s70, s70, 2
	s_add_u32 s46, s46, 0x100
	s_addc_u32 s47, s47, 0
	s_add_u32 s68, s68, 0x100
	s_addc_u32 s69, s69, 0
	s_cmp_gt_u32 s70, 29
	s_barrier
	s_cbranch_scc0 .LBB0_1223
	v_lshl_add_u32 v152, s44, 8, v146
	v_lshl_or_b32 v144, s65, 8, v148
	v_ashrrev_i32_e32 v153, 31, v152
	v_readlane_b32 s46, v254, 60
	v_ashrrev_i32_e32 v145, 31, v144
	v_lshlrev_b64 v[154:155], 14, v[152:153]
	v_readlane_b32 s47, v254, 61
	v_lshl_add_u64 v[154:155], s[46:47], 0, v[154:155]
	v_lshlrev_b64 v[156:157], 1, v[144:145]
	v_max_f32_e32 v120, 0, v120
	v_max_f32_e32 v121, 0, v121
	v_lshl_add_u64 v[144:145], v[154:155], 0, v[156:157]
	v_pk_mul_f32 v[154:155], v[120:121], v[120:121]
	v_max_f32_e32 v121, v122, v122
	v_max_f32_e32 v120, v126, v126
	v_max_f32_e32 v122, 0, v121
	v_max_f32_e32 v121, v127, v127
	v_max_f32_e32 v124, 0, v124
	v_max_f32_e32 v125, 0, v125
	v_max_f32_e32 v120, 0, v120
	v_max_f32_e32 v121, 0, v121
	v_max_f32_e32 v123, 0, v123
	v_pk_mul_f32 v[124:125], v[124:125], v[124:125]
	v_pk_mul_f32 v[126:127], v[120:121], v[120:121]
	v_pk_mul_f32 v[158:159], v[122:123], v[122:123]
	v_cvt_pk_bf16_f32 v120, v124, v125
	v_cvt_pk_bf16_f32 v121, v126, v127
	v_cvt_pk_bf16_f32 v122, v154, v155
	v_cvt_pk_bf16_f32 v123, v158, v159
	v_max_f32_e32 v112, 0, v112
	v_max_f32_e32 v113, 0, v113
	global_store_dwordx4 v[144:145], v[120:123], off
	s_nop 1
	v_pk_mul_f32 v[120:121], v[112:113], v[112:113]
	v_max_f32_e32 v113, v114, v114
	v_max_f32_e32 v112, v118, v118
	v_max_f32_e32 v114, 0, v113
	v_max_f32_e32 v113, v119, v119
	v_max_f32_e32 v116, 0, v116
	v_max_f32_e32 v117, 0, v117
	v_max_f32_e32 v112, 0, v112
	v_max_f32_e32 v113, 0, v113
	v_max_f32_e32 v115, 0, v115
	v_pk_mul_f32 v[116:117], v[116:117], v[116:117]
	v_pk_mul_f32 v[118:119], v[112:113], v[112:113]
	v_pk_mul_f32 v[122:123], v[114:115], v[114:115]
	v_cvt_pk_bf16_f32 v112, v116, v117
	v_cvt_pk_bf16_f32 v113, v118, v119
	v_cvt_pk_bf16_f32 v114, v120, v121
	v_cvt_pk_bf16_f32 v115, v122, v123
	v_max_f32_e32 v104, 0, v104
	v_max_f32_e32 v105, 0, v105
	global_store_dwordx4 v[144:145], v[112:115], off offset:256
	s_nop 1
	v_or_b32_e32 v112, 16, v152
	v_pk_mul_f32 v[114:115], v[104:105], v[104:105]
	v_max_f32_e32 v105, v106, v106
	v_ashrrev_i32_e32 v113, 31, v112
	v_max_f32_e32 v104, v110, v110
	v_max_f32_e32 v106, 0, v105
	v_max_f32_e32 v105, v111, v111
	v_lshlrev_b64 v[112:113], 14, v[112:113]
	v_max_f32_e32 v108, 0, v108
	v_max_f32_e32 v109, 0, v109
	v_max_f32_e32 v104, 0, v104
	v_max_f32_e32 v105, 0, v105
	v_max_f32_e32 v107, 0, v107
	v_lshl_add_u64 v[112:113], s[46:47], 0, v[112:113]
	v_pk_mul_f32 v[108:109], v[108:109], v[108:109]
	v_pk_mul_f32 v[110:111], v[104:105], v[104:105]
	v_pk_mul_f32 v[116:117], v[106:107], v[106:107]
	v_lshl_add_u64 v[112:113], v[112:113], 0, v[156:157]
	v_cvt_pk_bf16_f32 v104, v108, v109
	v_cvt_pk_bf16_f32 v105, v110, v111
	v_cvt_pk_bf16_f32 v106, v114, v115
	v_cvt_pk_bf16_f32 v107, v116, v117
	v_max_f32_e32 v96, 0, v96
	v_max_f32_e32 v97, 0, v97
	global_store_dwordx4 v[112:113], v[104:107], off
	s_nop 1
	v_pk_mul_f32 v[104:105], v[96:97], v[96:97]
	v_max_f32_e32 v97, v98, v98
; __device__ __forceinline__ unsigned cvt_pk_bf16(float lo, float hi) { const bf16x2_t r = __builtin_convertvector((f32x2){lo, hi}, bf16x2_t); return __builtin_bit_cast(unsigned, r); }
;     __device__ __forceinline__ void operator()(const AccT& acc, const Unit& u, int wr, int wc, int fr, int fq) const {
;     ...
;             for (int m = 0; m < 4; ++m) { bf16_t* rowp = O + (size_t)(row0 + ai * HALF + m * 16) * DFF + col0;
; #pragma unroll
;                 for (int bj = 0; bj < 2; ++bj) { f32x4 v0 = acc[ai][bj][m][0], v1 = acc[ai][bj][m][1];
; #pragma unroll
;                     for (int j = 0; j < 4; ++j) { float a = fmaxf(v0[j], 0.f), b = fmaxf(v1[j], 0.f); v0[j] = a * a; v1[j] = b * b; }
;                     u32x4 w; w.x = cvt_pk_bf16(v0[0], v0[1]); w.y = cvt_pk_bf16(v0[2], v0[3]); w.z = cvt_pk_bf16(v1[0], v1[1]); w.w = cvt_pk_bf16(v1[2], v1[3]);
;                     *(u32x4*)(rowp + bj * HALF) = w; } }
	v_max_f32_e32 v96, v102, v102
	v_max_f32_e32 v98, 0, v97
	v_max_f32_e32 v97, v103, v103
	v_max_f32_e32 v100, 0, v100
	v_max_f32_e32 v101, 0, v101
	v_max_f32_e32 v96, 0, v96
	v_max_f32_e32 v97, 0, v97
	v_max_f32_e32 v99, 0, v99
	v_pk_mul_f32 v[100:101], v[100:101], v[100:101]
	v_pk_mul_f32 v[102:103], v[96:97], v[96:97]
	v_pk_mul_f32 v[106:107], v[98:99], v[98:99]
	v_cvt_pk_bf16_f32 v96, v100, v101
	v_cvt_pk_bf16_f32 v97, v102, v103
	v_cvt_pk_bf16_f32 v98, v104, v105
	v_cvt_pk_bf16_f32 v99, v106, v107
	v_max_f32_e32 v88, 0, v88
	v_max_f32_e32 v89, 0, v89
	global_store_dwordx4 v[112:113], v[96:99], off offset:256
	s_nop 1
	v_or_b32_e32 v96, 32, v152
	v_pk_mul_f32 v[98:99], v[88:89], v[88:89]
	v_max_f32_e32 v89, v90, v90
	v_ashrrev_i32_e32 v97, 31, v96
	v_max_f32_e32 v88, v94, v94
	v_max_f32_e32 v90, 0, v89
	v_max_f32_e32 v89, v95, v95
	v_lshlrev_b64 v[96:97], 14, v[96:97]
	v_max_f32_e32 v92, 0, v92
	v_max_f32_e32 v93, 0, v93
	v_max_f32_e32 v88, 0, v88
	v_max_f32_e32 v89, 0, v89
	v_max_f32_e32 v91, 0, v91
	v_lshl_add_u64 v[96:97], s[46:47], 0, v[96:97]
	v_pk_mul_f32 v[92:93], v[92:93], v[92:93]
	v_pk_mul_f32 v[94:95], v[88:89], v[88:89]
	v_pk_mul_f32 v[100:101], v[90:91], v[90:91]
	v_lshl_add_u64 v[96:97], v[96:97], 0, v[156:157]
	v_cvt_pk_bf16_f32 v88, v92, v93
	v_cvt_pk_bf16_f32 v89, v94, v95
	v_cvt_pk_bf16_f32 v90, v98, v99
	v_cvt_pk_bf16_f32 v91, v100, v101
	v_max_f32_e32 v80, 0, v80
	v_max_f32_e32 v81, 0, v81
	global_store_dwordx4 v[96:97], v[88:91], off
	s_nop 1
	v_pk_mul_f32 v[88:89], v[80:81], v[80:81]
	v_max_f32_e32 v81, v82, v82
	v_max_f32_e32 v80, v86, v86
	v_max_f32_e32 v82, 0, v81
	v_max_f32_e32 v81, v87, v87
	v_max_f32_e32 v84, 0, v84
	v_max_f32_e32 v85, 0, v85
	v_max_f32_e32 v80, 0, v80
	v_max_f32_e32 v81, 0, v81
	v_max_f32_e32 v83, 0, v83
	v_pk_mul_f32 v[84:85], v[84:85], v[84:85]
	v_pk_mul_f32 v[86:87], v[80:81], v[80:81]
	v_pk_mul_f32 v[90:91], v[82:83], v[82:83]
	v_cvt_pk_bf16_f32 v80, v84, v85
	v_cvt_pk_bf16_f32 v81, v86, v87
	v_cvt_pk_bf16_f32 v82, v88, v89
	v_cvt_pk_bf16_f32 v83, v90, v91
	v_max_f32_e32 v72, 0, v72
	v_max_f32_e32 v73, 0, v73
	global_store_dwordx4 v[96:97], v[80:83], off offset:256
	s_nop 1
	v_or_b32_e32 v80, 48, v152
	v_pk_mul_f32 v[82:83], v[72:73], v[72:73]
	v_max_f32_e32 v73, v74, v74
	v_ashrrev_i32_e32 v81, 31, v80
	v_max_f32_e32 v72, v78, v78
	v_max_f32_e32 v74, 0, v73
	v_max_f32_e32 v73, v79, v79
	v_lshlrev_b64 v[80:81], 14, v[80:81]
	v_max_f32_e32 v76, 0, v76
	v_max_f32_e32 v77, 0, v77
	v_max_f32_e32 v72, 0, v72
	v_max_f32_e32 v73, 0, v73
	v_max_f32_e32 v75, 0, v75
	v_lshl_add_u64 v[80:81], s[46:47], 0, v[80:81]
	v_pk_mul_f32 v[76:77], v[76:77], v[76:77]
	v_pk_mul_f32 v[78:79], v[72:73], v[72:73]
	v_pk_mul_f32 v[84:85], v[74:75], v[74:75]
	v_lshl_add_u64 v[80:81], v[80:81], 0, v[156:157]
	v_cvt_pk_bf16_f32 v72, v76, v77
	v_cvt_pk_bf16_f32 v73, v78, v79
	v_cvt_pk_bf16_f32 v74, v82, v83
	v_cvt_pk_bf16_f32 v75, v84, v85
	v_max_f32_e32 v64, 0, v64
	v_max_f32_e32 v65, 0, v65
	global_store_dwordx4 v[80:81], v[72:75], off
	s_nop 1
	v_pk_mul_f32 v[72:73], v[64:65], v[64:65]
	v_max_f32_e32 v65, v66, v66
	v_max_f32_e32 v64, v70, v70
	v_max_f32_e32 v66, 0, v65
	v_max_f32_e32 v65, v71, v71
	v_max_f32_e32 v68, 0, v68
	v_max_f32_e32 v69, 0, v69
	v_max_f32_e32 v64, 0, v64
	v_max_f32_e32 v65, 0, v65
	v_max_f32_e32 v67, 0, v67
	v_pk_mul_f32 v[68:69], v[68:69], v[68:69]
	v_pk_mul_f32 v[70:71], v[64:65], v[64:65]
	v_pk_mul_f32 v[74:75], v[66:67], v[66:67]
	v_cvt_pk_bf16_f32 v64, v68, v69
	v_cvt_pk_bf16_f32 v65, v70, v71
	v_cvt_pk_bf16_f32 v66, v72, v73
	v_cvt_pk_bf16_f32 v67, v74, v75
	v_max_f32_e32 v56, 0, v56
	v_max_f32_e32 v57, 0, v57
	global_store_dwordx4 v[80:81], v[64:67], off offset:256
	s_nop 1
	v_pk_mul_f32 v[66:67], v[56:57], v[56:57]
	v_max_f32_e32 v57, v58, v58
	v_max_f32_e32 v60, 0, v60
	v_max_f32_e32 v61, 0, v61
	v_max_f32_e32 v56, v62, v62
	v_max_f32_e32 v58, 0, v57
	v_max_f32_e32 v57, v63, v63
	v_pk_mul_f32 v[60:61], v[60:61], v[60:61]
	v_max_f32_e32 v56, 0, v56
	v_max_f32_e32 v57, 0, v57
	v_max_f32_e32 v59, 0, v59
	v_pk_mul_f32 v[62:63], v[56:57], v[56:57]
	v_pk_mul_f32 v[68:69], v[58:59], v[58:59]
	v_cvt_pk_bf16_f32 v56, v60, v61
	v_add_co_u32_e32 v60, vcc, s61, v144
	v_cvt_pk_bf16_f32 v57, v62, v63
	v_cvt_pk_bf16_f32 v58, v66, v67
	v_cvt_pk_bf16_f32 v59, v68, v69
	v_addc_co_u32_e32 v61, vcc, 0, v145, vcc
	v_max_f32_e32 v48, 0, v48
	v_max_f32_e32 v49, 0, v49
	global_store_dwordx4 v[60:61], v[56:59], off
	s_nop 1
	v_pk_mul_f32 v[56:57], v[48:49], v[48:49]
	v_max_f32_e32 v49, v50, v50
	v_max_f32_e32 v48, v54, v54
	v_max_f32_e32 v50, 0, v49
	v_max_f32_e32 v49, v55, v55
	v_max_f32_e32 v52, 0, v52
	v_max_f32_e32 v53, 0, v53
	v_max_f32_e32 v48, 0, v48
	v_max_f32_e32 v49, 0, v49
	v_max_f32_e32 v51, 0, v51
	s_mov_b64 s[46:47], 0x200000
	v_pk_mul_f32 v[52:53], v[52:53], v[52:53]
	v_pk_mul_f32 v[54:55], v[48:49], v[48:49]
; __device__ __forceinline__ unsigned cvt_pk_bf16(float lo, float hi) { const bf16x2_t r = __builtin_convertvector((f32x2){lo, hi}, bf16x2_t); return __builtin_bit_cast(unsigned, r); }
; #define PG8_WAIT_V(n) asm volatile("s_waitcnt vmcnt(" #n ")" ::: "memory")
; #define PG8_BAR __builtin_amdgcn_s_barrier()
; template <class Epi>
; __device__ __forceinline__ void gemm_phase(LAS unsigned char* lds, const bf16_t* A, int lda, const bf16_t* Bt, int ldb, int M, int N, int K, int asel, const Epi& E, const int fixed_round = -1) {
;     ...
;         if (!has_next) break;
; #pragma unroll
;         for (int a = 0; a < 2; ++a)
; #pragma unroll
;             for (int b = 0; b < 2; ++b)
; #pragma unroll
;                 for (int m = 0; m < 4; ++m)
; #pragma unroll
;                     for (int n = 0; n < 2; ++n) acc[a][b][m][n] = (f32x4){0.f, 0.f, 0.f, 0.f};
;         cur = nxt; cA = nA; cB = nB; ++ui;
;     }
;     PG8_WAIT_V(0);
;     if (wr == 0) PG8_BAR;
;     PG8_BAR;
;     __device__ __forceinline__ void operator()(const AccT& acc, const Unit& u, int wr, int wc, int fr, int fq) const {
;     ...
;             for (int m = 0; m < 4; ++m) { bf16_t* rowp = O + (size_t)(row0 + ai * HALF + m * 16) * DFF + col0;
; #pragma unroll
;                 for (int bj = 0; bj < 2; ++bj) { f32x4 v0 = acc[ai][bj][m][0], v1 = acc[ai][bj][m][1];
; #pragma unroll
;                     for (int j = 0; j < 4; ++j) { float a = fmaxf(v0[j], 0.f), b = fmaxf(v1[j], 0.f); v0[j] = a * a; v1[j] = b * b; }
;                     u32x4 w; w.x = cvt_pk_bf16(v0[0], v0[1]); w.y = cvt_pk_bf16(v0[2], v0[3]); w.z = cvt_pk_bf16(v1[0], v1[1]); w.w = cvt_pk_bf16(v1[2], v1[3]);
;                     *(u32x4*)(rowp + bj * HALF) = w; } }
;     }
	v_pk_mul_f32 v[58:59], v[50:51], v[50:51]
	v_lshl_add_u64 v[64:65], v[144:145], 0, s[46:47]
	v_cvt_pk_bf16_f32 v48, v52, v53
	v_cvt_pk_bf16_f32 v49, v54, v55
	v_cvt_pk_bf16_f32 v50, v56, v57
	v_cvt_pk_bf16_f32 v51, v58, v59
	v_max_f32_e32 v40, 0, v40
	v_max_f32_e32 v41, 0, v41
	global_store_dwordx4 v[64:65], v[48:51], off offset:256
	s_nop 1
	v_pk_mul_f32 v[50:51], v[40:41], v[40:41]
	v_max_f32_e32 v41, v42, v42
	v_max_f32_e32 v44, 0, v44
	v_max_f32_e32 v45, 0, v45
	v_max_f32_e32 v40, v46, v46
	v_max_f32_e32 v42, 0, v41
	v_max_f32_e32 v41, v47, v47
	v_pk_mul_f32 v[44:45], v[44:45], v[44:45]
	v_max_f32_e32 v40, 0, v40
	v_max_f32_e32 v41, 0, v41
	v_max_f32_e32 v43, 0, v43
	v_pk_mul_f32 v[46:47], v[40:41], v[40:41]
	v_pk_mul_f32 v[52:53], v[42:43], v[42:43]
	v_cvt_pk_bf16_f32 v40, v44, v45
	v_add_co_u32_e32 v44, vcc, s62, v144
	v_cvt_pk_bf16_f32 v41, v46, v47
	v_cvt_pk_bf16_f32 v42, v50, v51
	v_cvt_pk_bf16_f32 v43, v52, v53
	v_addc_co_u32_e32 v45, vcc, 0, v145, vcc
	v_max_f32_e32 v32, 0, v32
	v_max_f32_e32 v33, 0, v33
	global_store_dwordx4 v[44:45], v[40:43], off
	s_nop 1
	v_pk_mul_f32 v[40:41], v[32:33], v[32:33]
	v_max_f32_e32 v33, v34, v34
	v_max_f32_e32 v32, v38, v38
	v_max_f32_e32 v34, 0, v33
	v_max_f32_e32 v33, v39, v39
	v_max_f32_e32 v36, 0, v36
	v_max_f32_e32 v37, 0, v37
	v_max_f32_e32 v32, 0, v32
	v_max_f32_e32 v33, 0, v33
	v_max_f32_e32 v35, 0, v35
	v_pk_mul_f32 v[36:37], v[36:37], v[36:37]
	v_pk_mul_f32 v[38:39], v[32:33], v[32:33]
	v_pk_mul_f32 v[42:43], v[34:35], v[34:35]
	v_lshl_add_u64 v[48:49], v[144:145], 0, s[4:5]
	v_cvt_pk_bf16_f32 v32, v36, v37
	v_cvt_pk_bf16_f32 v33, v38, v39
	v_cvt_pk_bf16_f32 v34, v40, v41
	v_cvt_pk_bf16_f32 v35, v42, v43
	v_max_f32_e32 v24, 0, v24
	v_max_f32_e32 v25, 0, v25
	global_store_dwordx4 v[48:49], v[32:35], off offset:256
	s_nop 1
	v_pk_mul_f32 v[34:35], v[24:25], v[24:25]
	v_max_f32_e32 v25, v26, v26
	v_max_f32_e32 v28, 0, v28
	v_max_f32_e32 v29, 0, v29
	v_max_f32_e32 v24, v30, v30
	v_max_f32_e32 v26, 0, v25
	v_max_f32_e32 v25, v31, v31
	v_pk_mul_f32 v[28:29], v[28:29], v[28:29]
	v_max_f32_e32 v24, 0, v24
	v_max_f32_e32 v25, 0, v25
	v_max_f32_e32 v27, 0, v27
	v_pk_mul_f32 v[30:31], v[24:25], v[24:25]
	v_pk_mul_f32 v[36:37], v[26:27], v[26:27]
	v_cvt_pk_bf16_f32 v24, v28, v29
	v_add_co_u32_e32 v28, vcc, s63, v144
	v_cvt_pk_bf16_f32 v25, v30, v31
	v_cvt_pk_bf16_f32 v26, v34, v35
	v_cvt_pk_bf16_f32 v27, v36, v37
	v_addc_co_u32_e32 v29, vcc, 0, v145, vcc
	v_max_f32_e32 v16, 0, v16
	v_max_f32_e32 v17, 0, v17
	global_store_dwordx4 v[28:29], v[24:27], off
	s_nop 1
	v_pk_mul_f32 v[24:25], v[16:17], v[16:17]
	v_max_f32_e32 v17, v18, v18
	v_max_f32_e32 v16, v22, v22
	v_max_f32_e32 v18, 0, v17
	v_max_f32_e32 v17, v23, v23
	v_max_f32_e32 v20, 0, v20
	v_max_f32_e32 v21, 0, v21
	v_max_f32_e32 v16, 0, v16
	v_max_f32_e32 v17, 0, v17
	v_max_f32_e32 v19, 0, v19
	v_pk_mul_f32 v[20:21], v[20:21], v[20:21]
	v_pk_mul_f32 v[22:23], v[16:17], v[16:17]
	v_pk_mul_f32 v[26:27], v[18:19], v[18:19]
	v_lshl_add_u64 v[32:33], v[144:145], 0, s[6:7]
	v_cvt_pk_bf16_f32 v16, v20, v21
	v_cvt_pk_bf16_f32 v17, v22, v23
	v_cvt_pk_bf16_f32 v18, v24, v25
	v_cvt_pk_bf16_f32 v19, v26, v27
	v_max_f32_e32 v8, 0, v8
	v_max_f32_e32 v9, 0, v9
	global_store_dwordx4 v[32:33], v[16:19], off offset:256
	s_nop 1
	v_pk_mul_f32 v[18:19], v[8:9], v[8:9]
	v_max_f32_e32 v9, v10, v10
	v_max_f32_e32 v12, 0, v12
	v_max_f32_e32 v13, 0, v13
	v_max_f32_e32 v8, v14, v14
	v_max_f32_e32 v10, 0, v9
	v_max_f32_e32 v9, v15, v15
	v_pk_mul_f32 v[12:13], v[12:13], v[12:13]
	v_max_f32_e32 v8, 0, v8
	v_max_f32_e32 v9, 0, v9
	v_max_f32_e32 v11, 0, v11
	v_pk_mul_f32 v[14:15], v[8:9], v[8:9]
	v_pk_mul_f32 v[20:21], v[10:11], v[10:11]
	v_cvt_pk_bf16_f32 v8, v12, v13
	v_add_co_u32_e32 v12, vcc, s64, v144
	v_cvt_pk_bf16_f32 v9, v14, v15
	v_cvt_pk_bf16_f32 v10, v18, v19
	v_cvt_pk_bf16_f32 v11, v20, v21
	v_addc_co_u32_e32 v13, vcc, 0, v145, vcc
	v_max_f32_e32 v0, 0, v0
	v_max_f32_e32 v1, 0, v1
	global_store_dwordx4 v[12:13], v[8:11], off
	s_nop 1
	v_pk_mul_f32 v[8:9], v[0:1], v[0:1]
	v_max_f32_e32 v1, v2, v2
	v_max_f32_e32 v0, v6, v6
	v_max_f32_e32 v2, 0, v1
	v_max_f32_e32 v1, v7, v7
	v_max_f32_e32 v4, 0, v4
	v_max_f32_e32 v5, 0, v5
	v_max_f32_e32 v0, 0, v0
	v_max_f32_e32 v1, 0, v1
	v_max_f32_e32 v3, 0, v3
	v_pk_mul_f32 v[4:5], v[4:5], v[4:5]
	v_pk_mul_f32 v[6:7], v[0:1], v[0:1]
	v_pk_mul_f32 v[10:11], v[2:3], v[2:3]
	v_lshl_add_u64 v[16:17], v[144:145], 0, s[22:23]
	v_cvt_pk_bf16_f32 v0, v4, v5
	v_cvt_pk_bf16_f32 v1, v6, v7
	v_cvt_pk_bf16_f32 v2, v8, v9
	v_cvt_pk_bf16_f32 v3, v10, v11
	s_and_b64 vcc, exec, s[0:1]
	s_mov_b32 s65, s24
	s_mov_b32 s44, s28
	s_mov_b64 s[48:49], s[42:43]
	s_mov_b64 s[46:47], s[40:41]
	s_mov_b64 s[70:71], s[26:27]
	global_store_dwordx4 v[16:17], v[0:3], off offset:256
	s_cbranch_vccz .LBB0_1216
	s_waitcnt vmcnt(0)
	s_cmpk_gt_u32 s33, 0xff
	s_cbranch_scc1 .LBB0_1227
	s_barrier
